# second V cache in MFMA B-fragment order (written by a short pass after POST): FIXREF attention reads each V fragment with one ds_read_b128 instead of two ds_read_b64_tr_b16
# speedup vs baseline: 1.0110x; 1.0110x over previous
;   #define DMA_K(t,slot) glds16(ksrc+(long)(t)*4096,(unsigned)__builtin_amdgcn_readfirstlane(kdst+(slot)))
;   #define DMA_V(t,slot) glds16(vsrc+(long)(t)*4096,(unsigned)__builtin_amdgcn_readfirstlane(vdst+(slot)))
; template<int THRL,bool FIXREF> __device__ __forceinline__ void attn_unit(const float*gq,const float*tab,const int tq0,const bf16*Qw0,const bf16*__restrict__ Kl,const bf16*__restrict__ Vl,const int NT,bf16*Ow0,char*shm){
;   int tid_l=threadIdx.x; asm volatile("":"+v"(tid_l)); const int tid=tid_l,lane=tid&63,r32=lane&31,hi=lane>>5; const int wid=__builtin_amdgcn_readfirstlane(tid>>6);
;   const bf16*Qw=Qw0+(long)(wid*QBLK)*QP;
;   const unsigned lds0=(unsigned)(uintptr_t)shm;
;   float*wsf=(float*)(shm+LDS_WS)+wid*64;
;   const bf16*ksrc=Kl+wid*512+lane*8;
;   const bf16*vsrc=Vl+wid*512+lane*8;
;   const unsigned kdst=lds0+LDS_K+wid*1024, vdst=lds0+LDS_V+wid*1024;
;     ...
;   const int vb0=(int)(lds0+LDS_V)+((lane>>4)&1)*32+(lane&3)*8+(4*hi+((lane&15)>>2))*64;
;   const char*Kbase=shm+LDS_K; bf16x8 kf[8];
;   const lds_cptr shm3=(lds_cptr)shm; const lds_cptr kp0=shm3+LDS_K+hi*1024+r32*16; const lds_cptr vp0=shm3+LDS_V+((lane>>4)&1)*32+(lane&3)*8+(4*hi+((lane&15)>>2))*64;
;   DMA_K(0,0);DMA_V(0,0);DMA_K(1,SLOTB);
;   bf16x8 qr[4];
;   {
;     float xq[4][8]; float ss=0.f;
;     #pragma unroll
;     for(int d0=0;d0<4;++d0){ const u32x4 w=*reinterpret_cast<const u32x4*>(&Qw[(long)r32*QP+d0*16+hi*8]); const unsigned ww[4]={w.x,w.y,w.z,w.w};
;       #pragma unroll
;       for(int c=0;c<4;++c){ xq[d0][2*c]=__uint_as_float(ww[c]<<16); xq[d0][2*c+1]=__uint_as_float(ww[c]&0xffff0000u); ss+=xq[d0][2*c]*xq[d0][2*c]+xq[d0][2*c+1]*xq[d0][2*c+1]; } }
;     { auto rr=__builtin_amdgcn_permlane32_swap(__float_as_uint(ss),__float_as_uint(ss),false,false); ss=__uint_as_float(rr[0])+__uint_as_float(rr[1]); }
;     const float rstd=__builtin_amdgcn_rsqf(ss*(1.f/64.f)+1e-6f)*C2;
.LBB0_273:
	s_and_b64 vcc, exec, s[14:15]
	s_cbranch_vccz .LBB0_284
	v_mov_b32_e32 v84, v214
	s_nop 0
	v_readfirstlane_b32 s29, v84
	s_ashr_i32 s28, s29, 6
	s_lshl_b32 s40, s28, 5
	s_ashr_i32 s41, s40, 31
	s_mul_i32 s7, s28, 0x28000
	s_mul_hi_i32 s10, s40, 0x1400
	s_add_u32 s14, s50, s7
	s_addc_u32 s15, s51, s10
	s_lshl_b32 s30, s28, 9
	s_ashr_i32 s31, s30, 31
	s_lshl_b64 s[30:31], s[30:31], 1
	s_add_u32 s38, s60, s30
	s_addc_u32 s39, s61, s31
	s_add_u32 s18, s18, s30
	s_addc_u32 s19, s19, s31
	s_sub_u32 s18, s18, 0x28a0000
	s_subb_u32 s19, s19, 0
	s_lshl_b32 s7, s28, 10
	v_and_b32_e32 v226, 63, v84
	v_lshlrev_b32_e32 v240, 4, v226
	s_cmp_lg_u32 0, -1
	v_lshlrev_b32_e32 v0, 4, v226
	s_cselect_b32 s10, 0, 0
	v_lshl_add_u64 v[194:195], s[38:39], 0, v[0:1]
	v_lshl_add_u64 v[50:51], s[18:19], 0, v[0:1]
	s_add_i32 s18, s7, s10
	s_mov_b32 s10, m0
	s_mov_b32 m0, s18
	s_nop 0
	global_load_lds_dwordx4 v[194:195], off
	s_mov_b32 m0, s10
	s_mov_b64 s[30:31], 0x2000
	v_and_b32_e32 v227, 31, v84
	v_bfe_u32 v228, v84, 5, 1
	s_add_i32 s19, s18, 0x6000
	s_mov_b32 s10, m0
	s_mov_b32 m0, s19
	s_nop 0
	global_load_lds_dwordx4 v[50:51], off
	s_mov_b32 m0, s10
	v_lshl_add_u64 v[2:3], v[194:195], 0, s[30:31]
	s_add_i32 s10, s18, 0x2000
	s_mov_b32 s30, m0
	s_mov_b32 m0, s10
	s_nop 0
	global_load_lds_dwordx4 v[2:3], off
	s_mov_b32 m0, s30
	v_mul_u32_u24_e32 v2, 0xa00, v227
	v_lshlrev_b32_e32 v0, 3, v228
	v_or_b32_e32 v2, v0, v2
	v_lshlrev_b32_e32 v6, 1, v2
	global_load_dwordx4 v[18:21], v6, s[14:15]
	global_load_dwordx4 v[26:29], v6, s[14:15] offset:32
	global_load_dwordx4 v[2:5], v6, s[14:15] offset:64
	global_load_dwordx4 v[22:25], v6, s[14:15] offset:96
	v_and_b32_e32 v43, 32, v84
	s_cmp_eq_u64 s[4:5], 0
	s_waitcnt vmcnt(3)
	v_and_b32_e32 v55, 0xffff0000, v19
	v_and_b32_e32 v73, 0xffff0000, v18
	v_and_b32_e32 v39, 0xffff0000, v20
	v_lshlrev_b32_e32 v54, 16, v19
	v_mul_f32_e32 v34, v55, v55
	v_lshlrev_b32_e32 v72, 16, v18
	v_mul_f32_e32 v18, v73, v73
	v_and_b32_e32 v41, 0xffff0000, v21
	v_lshlrev_b32_e32 v38, 16, v20
	v_mul_f32_e32 v6, v39, v39
	v_pk_fma_f32 v[34:35], v[54:55], v[54:55], v[34:35] op_sel_hi:[1,1,0]
	v_pk_fma_f32 v[18:19], v[72:73], v[72:73], v[18:19] op_sel_hi:[1,1,0]
	s_waitcnt vmcnt(1)
	v_lshlrev_b32_e32 v60, 16, v2
	v_and_b32_e32 v53, 0xffff0000, v2
	v_lshlrev_b32_e32 v40, 16, v21
	v_mul_f32_e32 v2, v41, v41
	v_pk_fma_f32 v[20:21], v[38:39], v[38:39], v[6:7] op_sel_hi:[1,1,0]
	v_and_b32_e32 v69, 0xffff0000, v26
	v_pk_add_f32 v[18:19], v[18:19], v[34:35]
	v_pk_fma_f32 v[30:31], v[40:41], v[40:41], v[2:3] op_sel_hi:[1,1,0]
	v_and_b32_e32 v63, 0xffff0000, v29
	v_and_b32_e32 v57, 0xffff0000, v27
	v_lshlrev_b32_e32 v68, 16, v26
	v_mul_f32_e32 v26, v69, v69
	v_pk_add_f32 v[18:19], v[20:21], v[18:19]
	v_lshlrev_b32_e32 v62, 16, v29
	v_mul_f32_e32 v2, v63, v63
	v_and_b32_e32 v59, 0xffff0000, v28
	v_lshlrev_b32_e32 v56, 16, v27
	v_mul_f32_e32 v36, v57, v57
	v_pk_fma_f32 v[26:27], v[68:69], v[68:69], v[26:27] op_sel_hi:[1,1,0]
	v_pk_add_f32 v[18:19], v[30:31], v[18:19]
	v_lshlrev_b32_e32 v48, 16, v3
	v_and_b32_e32 v67, 0xffff0000, v3
	v_lshlrev_b32_e32 v44, 16, v4
	v_and_b32_e32 v65, 0xffff0000, v4
	v_lshlrev_b32_e32 v42, 16, v5
	v_and_b32_e32 v47, 0xffff0000, v5
	v_pk_fma_f32 v[32:33], v[62:63], v[62:63], v[2:3] op_sel_hi:[1,1,0]
	global_load_dwordx4 v[2:5], v43, s[44:45] offset:16
	global_load_dwordx4 v[10:13], v43, s[44:45]
	v_lshlrev_b32_e32 v58, 16, v28
	v_mul_f32_e32 v6, v59, v59
	v_pk_fma_f32 v[36:37], v[56:57], v[56:57], v[36:37] op_sel_hi:[1,1,0]
	v_pk_add_f32 v[18:19], v[26:27], v[18:19]
	v_pk_fma_f32 v[28:29], v[58:59], v[58:59], v[6:7] op_sel_hi:[1,1,0]
	global_load_dwordx4 v[6:9], v43, s[44:45] offset:80
	global_load_dwordx4 v[14:17], v43, s[44:45] offset:64
	v_pk_add_f32 v[18:19], v[36:37], v[18:19]
	s_waitcnt vmcnt(4)
	v_and_b32_e32 v71, 0xffff0000, v22
	v_pk_add_f32 v[18:19], v[28:29], v[18:19]
	v_mov_b32_e32 v61, v71
	v_mul_f32_e32 v20, v53, v53
	v_pk_add_f32 v[18:19], v[32:33], v[18:19]
	v_pk_fma_f32 v[20:21], v[60:61], v[60:61], v[20:21] op_sel_hi:[1,1,0]
	v_lshlrev_b32_e32 v70, 16, v22
	v_pk_add_f32 v[76:77], v[20:21], v[18:19]
	global_load_dwordx4 v[18:21], v43, s[44:45] offset:144
	global_load_dwordx4 v[34:37], v43, s[44:45] offset:128
	global_load_dwordx4 v[26:29], v43, s[44:45] offset:208
	global_load_dwordx4 v[30:33], v43, s[44:45] offset:192
	v_mul_f32_e32 v22, v71, v71
	v_and_b32_e32 v81, 0xffff0000, v23
	v_pk_fma_f32 v[74:75], v[70:71], v[70:71], v[22:23] op_sel_hi:[1,1,0]
	v_mov_b32_e32 v49, v81
	v_mul_f32_e32 v22, v67, v67
	v_and_b32_e32 v87, 0xffff0000, v24
	v_lshlrev_b32_e32 v80, 16, v23
	v_pk_fma_f32 v[22:23], v[48:49], v[48:49], v[22:23] op_sel_hi:[1,1,0]
	v_lshlrev_b32_e32 v86, 16, v24
	v_mov_b32_e32 v45, v87
	v_mul_f32_e32 v24, v65, v65
	v_and_b32_e32 v91, 0xffff0000, v25
	v_pk_add_f32 v[22:23], v[22:23], v[76:77]
	v_pk_fma_f32 v[88:89], v[44:45], v[44:45], v[24:25] op_sel_hi:[1,1,0]
	v_mov_b32_e32 v43, v91
	v_mul_f32_e32 v24, v47, v47
	v_pk_add_f32 v[22:23], v[88:89], v[22:23]
	v_lshlrev_b32_e32 v90, 16, v25
	v_pk_fma_f32 v[24:25], v[42:43], v[42:43], v[24:25] op_sel_hi:[1,1,0]
	v_mul_f32_e32 v46, v81, v81
	v_mov_b32_e32 v94, v91
	v_mov_b32_e32 v95, v87
	v_pk_add_f32 v[22:23], v[24:25], v[22:23]
	v_pk_fma_f32 v[82:83], v[80:81], v[80:81], v[46:47] op_sel_hi:[1,1,0]
	v_mov_b32_e32 v92, v90
	v_mov_b32_e32 v93, v86
	v_pk_mul_f32 v[94:95], v[94:95], v[94:95]
	v_pk_add_f32 v[22:23], v[74:75], v[22:23]
	v_pk_fma_f32 v[92:93], v[92:93], v[92:93], v[94:95]
	v_pk_add_f32 v[22:23], v[82:83], v[22:23]
	v_mov_b32_e32 v66, v80
	v_pk_add_f32 v[22:23], v[92:93], v[22:23] op_sel:[1,0] op_sel_hi:[0,1]
	v_pk_add_f32 v[22:23], v[92:93], v[22:23]
	v_mov_b32_e32 v52, v70
	v_mov_b32_e32 v23, v22
	s_nop 1
	v_permlane32_swap_b32_e32 v22, v23
	v_add_f32_e32 v22, v22, v23
	v_fmamk_f32 v22, v22, 0x3c800000, v215
	v_rsq_f32_e32 v22, v22
	v_mov_b32_e32 v64, v86
	v_mov_b32_e32 v46, v90
	v_mul_f32_e32 v92, 0x3e38aa3b, v22
	s_waitcnt vmcnt(7)
; __device__ __forceinline__ unsigned cvtpk_s(float lo,float hi){f32x2_t v={lo,hi};bf16x2_t b=__builtin_convertvector(v,bf16x2_t);return __builtin_bit_cast(unsigned,b);}
; template<int THRL,bool FIXREF> __device__ __forceinline__ void attn_unit(const float*gq,const float*tab,const int tq0,const bf16*Qw0,const bf16*__restrict__ Kl,const bf16*__restrict__ Vl,const int NT,bf16*Ow0,char*shm){
;     ...
;     const float rstd=__builtin_amdgcn_rsqf(ss*(1.f/64.f)+1e-6f)*C2;
;     #pragma unroll
;     for(int d0=0;d0<4;++d0){ const float*gp=gq+d0*16+hi*8;
;       #pragma unroll
;       for(int j=0;j<8;++j)xq[d0][j]*=rstd*gp[j]; }
;     if(tab){ const int tpos=(tq0+wid*QBLK+r32)&16383; const float*tr_=tab+((tpos>>6)*16+hi*8)*2; const float*tc_=tab+((tpos&63)*16+hi*8)*2;
;       #pragma unroll
;       for(int j=0;j<8;++j){ const float cr=tr_[2*j],sr=tr_[2*j+1],cc=tc_[2*j],sc=tc_[2*j+1];
;         const float a0=xq[0][j],b0=xq[1][j],a1=xq[2][j],b1=xq[3][j];
;         xq[0][j]=a0*cr-b0*sr; xq[1][j]=a0*sr+b0*cr; xq[2][j]=a1*cc-b1*sc; xq[3][j]=a1*sc+b1*cc; } }
;     #pragma unroll
;     for(int d0=0;d0<4;++d0){ u32x4 p; p.x=cvtpk_s(xq[d0][0],xq[d0][1]); p.y=cvtpk_s(xq[d0][2],xq[d0][3]); p.z=cvtpk_s(xq[d0][4],xq[d0][5]); p.w=cvtpk_s(xq[d0][6],xq[d0][7]); qr[d0]=__builtin_bit_cast(bf16x8,p); } }
	v_pk_mul_f32 v[2:3], v[2:3], v[92:93] op_sel_hi:[1,0]
	s_waitcnt vmcnt(6)
	v_pk_mul_f32 v[10:11], v[10:11], v[92:93] op_sel_hi:[1,0]
	v_pk_mul_f32 v[38:39], v[2:3], v[38:39]
	v_pk_mul_f32 v[2:3], v[92:93], v[4:5] op_sel_hi:[0,1]
	v_pk_mul_f32 v[22:23], v[10:11], v[72:73]
	v_pk_mul_f32 v[10:11], v[12:13], v[92:93] op_sel_hi:[1,0]
	v_pk_mul_f32 v[40:41], v[2:3], v[40:41]
	s_waitcnt vmcnt(4)
	v_pk_mul_f32 v[2:3], v[92:93], v[14:15] op_sel_hi:[0,1]
	v_pk_mul_f32 v[24:25], v[10:11], v[54:55]
	v_pk_mul_f32 v[54:55], v[2:3], v[68:69]
	v_pk_mul_f32 v[2:3], v[92:93], v[16:17] op_sel_hi:[0,1]
	v_pk_mul_f32 v[56:57], v[2:3], v[56:57]
	v_pk_mul_f32 v[2:3], v[92:93], v[6:7] op_sel_hi:[0,1]
	v_pk_mul_f32 v[58:59], v[2:3], v[58:59]
	v_pk_mul_f32 v[2:3], v[92:93], v[8:9] op_sel_hi:[0,1]
	s_waitcnt vmcnt(2)
	v_mov_b32_e32 v78, v34
	v_pk_mul_f32 v[62:63], v[2:3], v[62:63]
	s_waitcnt vmcnt(0)
	v_mov_b32_e32 v79, v31
	v_pk_mul_f32 v[2:3], v[92:93], v[78:79] op_sel_hi:[0,1]
	v_mov_b32_e32 v76, v36
	v_mov_b32_e32 v36, v32
	v_pk_mul_f32 v[82:83], v[2:3], v[60:61]
	v_pk_mul_f32 v[2:3], v[92:93], v[32:33] op_sel_hi:[0,1]
	v_mov_b32_e32 v34, v30
	v_mov_b32_e32 v77, v33
	v_mov_b32_e32 v88, v18
	v_mov_b32_e32 v89, v27
	v_mov_b32_e32 v18, v26
	v_pk_mul_f32 v[8:9], v[92:93], v[36:37] op_sel_hi:[0,1]
	v_mov_b32_e32 v14, v20
	v_mov_b32_e32 v15, v29
	v_mov_b32_e32 v20, v28
	v_pk_mul_f32 v[60:61], v[2:3], v[80:81]
	v_pk_mul_f32 v[2:3], v[92:93], v[26:27] op_sel_hi:[0,1]
	v_pk_mul_f32 v[4:5], v[92:93], v[34:35] op_sel_hi:[0,1]
	v_pk_mul_f32 v[6:7], v[92:93], v[76:77] op_sel_hi:[0,1]
	v_pk_mul_f32 v[10:11], v[92:93], v[88:89] op_sel_hi:[0,1]
	v_pk_mul_f32 v[12:13], v[92:93], v[18:19] op_sel_hi:[0,1]
	v_pk_mul_f32 v[14:15], v[92:93], v[14:15] op_sel_hi:[0,1]
	v_pk_mul_f32 v[16:17], v[92:93], v[20:21] op_sel_hi:[0,1]
	v_pk_mul_f32 v[18:19], v[92:93], v[30:31] op_sel_hi:[0,1]
	v_pk_mul_f32 v[72:73], v[8:9], v[66:67]
	v_pk_mul_f32 v[66:67], v[2:3], v[86:87]
	v_pk_mul_f32 v[2:3], v[92:93], v[28:29] op_sel_hi:[0,1]
	v_pk_mul_f32 v[68:69], v[4:5], v[52:53]
	v_pk_mul_f32 v[52:53], v[18:19], v[70:71]
	v_pk_mul_f32 v[80:81], v[6:7], v[48:49]
	v_pk_mul_f32 v[74:75], v[12:13], v[64:65]
	v_pk_mul_f32 v[78:79], v[10:11], v[44:45]
	v_pk_mul_f32 v[70:71], v[16:17], v[46:47]
	v_pk_mul_f32 v[64:65], v[2:3], v[90:91]
	v_pk_mul_f32 v[76:77], v[14:15], v[42:43]
	s_cbranch_scc1 .LBB0_276
	s_add_i32 s6, s40, s6
	v_add_u32_e32 v2, s6, v227
	v_lshrrev_b32_e32 v3, 2, v2
	s_movk_i32 s6, 0xff0
	v_and_or_b32 v3, v3, s6, v0
	v_lshlrev_b32_e32 v2, 4, v2
	s_movk_i32 s6, 0x3f0
	v_and_or_b32 v0, v2, s6, v0
	v_lshlrev_b32_e32 v85, 3, v3
	v_lshlrev_b32_e32 v0, 3, v0
	global_load_dwordx4 v[2:5], v0, s[4:5] offset:48
	global_load_dwordx4 v[6:9], v0, s[4:5] offset:32
	global_load_dwordx4 v[14:17], v0, s[4:5] offset:16
	global_load_dwordx4 v[44:47], v0, s[4:5]
	global_load_dwordx4 v[10:13], v85, s[4:5] offset:48
	global_load_dwordx4 v[18:21], v85, s[4:5] offset:32
	global_load_dwordx4 v[86:89], v85, s[4:5] offset:16
	global_load_dwordx4 v[90:93], v85, s[4:5]
	v_mov_b32_e32 v37, v69
	v_mov_b32_e32 v36, v82
	v_mov_b32_e32 v32, v80
	v_mov_b32_e32 v33, v73
	v_mov_b32_e32 v30, v78
	v_mov_b32_e32 v31, v75
	v_mov_b32_e32 v26, v76
	v_mov_b32_e32 v27, v71
	s_waitcnt vmcnt(7)
	v_mov_b32_e32 v28, v3
	s_waitcnt vmcnt(6)
	v_mov_b32_e32 v34, v7
	s_waitcnt vmcnt(5)
	v_mov_b32_e32 v42, v15
	s_waitcnt vmcnt(4)
	v_mov_b32_e32 v48, v45
	s_waitcnt vmcnt(0)
	v_mov_b32_e32 v94, v91
	v_mov_b32_e32 v95, v93
	v_pk_mul_f32 v[96:97], v[22:23], v[94:95]
	v_mov_b32_e32 v91, v92
	v_pk_mul_f32 v[92:93], v[54:55], v[94:95]
	v_pk_fma_f32 v[54:55], v[54:55], v[90:91], v[96:97]
	v_pk_fma_f32 v[22:23], v[22:23], v[90:91], v[92:93] neg_lo:[0,0,1] neg_hi:[0,0,1]
	v_mov_b32_e32 v90, v44
	v_mov_b32_e32 v91, v47
	v_pk_mul_f32 v[90:91], v[68:69], v[90:91]
	v_mov_b32_e32 v68, v45
	v_mov_b32_e32 v69, v47
	v_pk_mul_f32 v[52:53], v[52:53], v[68:69]
	v_mov_b32_e32 v45, v46
	v_pk_fma_f32 v[68:69], v[36:37], v[44:45], v[52:53] neg_lo:[0,0,1] neg_hi:[0,0,1]
	v_mov_b32_e32 v36, v87
	v_mov_b32_e32 v37, v89
	v_pk_mul_f32 v[44:45], v[24:25], v[36:37]
	v_mov_b32_e32 v87, v88
	v_pk_mul_f32 v[36:37], v[56:57], v[36:37]
	v_pk_fma_f32 v[56:57], v[56:57], v[86:87], v[44:45]
	v_mov_b32_e32 v44, v15
	v_mov_b32_e32 v45, v17
	v_pk_fma_f32 v[24:25], v[24:25], v[86:87], v[36:37] neg_lo:[0,0,1] neg_hi:[0,0,1]
	v_mov_b32_e32 v36, v14
	v_mov_b32_e32 v37, v17
	v_pk_mul_f32 v[44:45], v[60:61], v[44:45]
	v_mov_b32_e32 v15, v16
	v_pk_mul_f32 v[36:37], v[72:73], v[36:37]
	v_pk_fma_f32 v[72:73], v[32:33], v[14:15], v[44:45] neg_lo:[0,0,1] neg_hi:[0,0,1]
	v_mov_b32_e32 v14, v19
	v_mov_b32_e32 v15, v21
	v_mov_b32_e32 v43, v16
	v_pk_mul_f32 v[16:17], v[38:39], v[14:15]
	v_mov_b32_e32 v19, v20
	v_pk_mul_f32 v[14:15], v[58:59], v[14:15]
	v_pk_fma_f32 v[58:59], v[58:59], v[18:19], v[16:17]
	v_mov_b32_e32 v16, v7
	v_mov_b32_e32 v17, v9
	v_pk_fma_f32 v[38:39], v[38:39], v[18:19], v[14:15] neg_lo:[0,0,1] neg_hi:[0,0,1]
	v_mov_b32_e32 v14, v6
	v_mov_b32_e32 v15, v9
	v_pk_mul_f32 v[16:17], v[66:67], v[16:17]
	v_mov_b32_e32 v7, v8
	v_pk_mul_f32 v[14:15], v[74:75], v[14:15]
	v_pk_fma_f32 v[74:75], v[30:31], v[6:7], v[16:17] neg_lo:[0,0,1] neg_hi:[0,0,1]
	v_mov_b32_e32 v6, v11
	v_mov_b32_e32 v7, v13
	v_mov_b32_e32 v35, v8
	v_pk_mul_f32 v[8:9], v[40:41], v[6:7]
	v_mov_b32_e32 v11, v12
	v_pk_mul_f32 v[6:7], v[62:63], v[6:7]
	v_pk_fma_f32 v[62:63], v[62:63], v[10:11], v[8:9]
	v_mov_b32_e32 v8, v3
	v_mov_b32_e32 v9, v5
	v_pk_fma_f32 v[40:41], v[40:41], v[10:11], v[6:7] neg_lo:[0,0,1] neg_hi:[0,0,1]
	v_mov_b32_e32 v6, v2
	v_mov_b32_e32 v7, v5
	v_pk_mul_f32 v[8:9], v[64:65], v[8:9]
	v_mov_b32_e32 v3, v4
	v_mov_b32_e32 v49, v46
	v_mov_b32_e32 v29, v4
	v_pk_mul_f32 v[6:7], v[70:71], v[6:7]
	v_pk_fma_f32 v[70:71], v[26:27], v[2:3], v[8:9] neg_lo:[0,0,1] neg_hi:[0,0,1]
	v_pk_fma_f32 v[52:53], v[82:83], v[48:49], v[90:91]
	v_pk_fma_f32 v[60:61], v[80:81], v[42:43], v[36:37]
	v_pk_fma_f32 v[66:67], v[78:79], v[34:35], v[14:15]
	v_pk_fma_f32 v[64:65], v[76:77], v[28:29], v[6:7]
	v_mov_b32_e32 v82, v68
	v_mov_b32_e32 v80, v72
	v_mov_b32_e32 v78, v74
	v_mov_b32_e32 v76, v70
; #define WAIT_BAR(N) asm volatile("s_waitcnt vmcnt(" #N ") lgkmcnt(0)\n\ts_barrier":::"memory")
;   #define DMA_K(t,slot) glds16(ksrc+(long)(t)*4096,(unsigned)__builtin_amdgcn_readfirstlane(kdst+(slot)))
;   #define DMA_V(t,slot) glds16(vsrc+(long)(t)*4096,(unsigned)__builtin_amdgcn_readfirstlane(vdst+(slot)))
;   #define CMASK(P0,P1,t) do{}while(0)
;   #define ROT() do{sl_prev=sl_cur;sl_cur=sl_next;sl_next=(sl_next==(NSLOT-1)*SLOTB)?0:sl_next+SLOTB;}while(0)
;   #define CMASK(P0,P1,t) do{}while(0)
;   #define CMASK(P0,P1,t) do{}while(0)
; template<int THRL,bool FIXREF> __device__ __forceinline__ void attn_unit(const float*gq,const float*tab,const int tq0,const bf16*Qw0,const bf16*__restrict__ Kl,const bf16*__restrict__ Vl,const int NT,bf16*Ow0,char*shm){
;     ...
;   float mhat=0.f,l_reg=0.f;f32x16 o[2];o[0]=f32x16{};o[1]=f32x16{};f32x16 negm=f32x16{};asm volatile("":"+v"(negm));
;     ...
;   bool resc=false;
;     ...
;   f32x16 pA0,pA1,pB0,pB1;
;   int sl_prev=0,sl_cur=0,sl_next=SLOTB;
;     ...
;   DMA_K(2,2*SLOTB);
;   WAIT_BAR(3);
;   qkt(pA0,pA1,Kbase,qr,negm,r32,hi);asm volatile("s_nop 15\n\ts_nop 7":"+v"(pA0),"+v"(pA1));CMASK(pA0,pA1,0);
;   START(pA0,pA1);
;   _Pragma("unroll") for(int r=0;r<16;++r)pA1[r]=__builtin_amdgcn_exp2f(pA1[r]);
;   WAIT_BAR(0);
;   DMA_K(3,0);DMA_V(1,SLOTB);
;   ROT();
;   kload8(kf,kp0+sl_cur);
;   WAIT_BAR(2);
.LBB0_276:
	v_lshlrev_b32_e32 v0, 10, v228
	v_lshlrev_b32_e32 v2, 4, v227
	v_add3_u32 v230, 0, v0, v2
	v_mov_b32_e32 v2, v1
	v_mov_b32_e32 v3, v1
	v_mov_b32_e32 v4, v1
	v_mov_b32_e32 v5, v1
	v_mov_b32_e32 v6, v1
	v_mov_b32_e32 v7, v1
	v_mov_b32_e32 v8, v1
	v_mov_b32_e32 v9, v1
	v_mov_b32_e32 v10, v1
	v_mov_b32_e32 v11, v1
	v_mov_b32_e32 v12, v1
	v_mov_b32_e32 v13, v1
	v_mov_b32_e32 v14, v1
	v_mov_b32_e32 v15, v1
	s_cmp_lg_u32 0, -1
	v_mov_b32_e32 v0, v1
	v_mov_b64_e32 v[16:17], v[14:15]
	s_cselect_b32 s4, 0, 0
	v_mov_b64_e32 v[14:15], v[12:13]
	v_mov_b64_e32 v[12:13], v[10:11]
	v_mov_b64_e32 v[10:11], v[8:9]
	v_mov_b64_e32 v[8:9], v[6:7]
	v_mov_b64_e32 v[6:7], v[4:5]
	v_mov_b64_e32 v[4:5], v[2:3]
	v_mov_b64_e32 v[2:3], v[0:1]
	s_add_i32 s5, s4, s7
	v_lshl_add_u64 v[18:19], v[194:195], 0, s[16:17]
	s_add_i32 s4, s5, 0x4000
	s_mov_b32 s6, m0
	s_mov_b32 m0, s4
	s_nop 0
	global_load_lds_dwordx4 v[18:19], off
	s_mov_b32 m0, s6
	s_waitcnt vmcnt(3) lgkmcnt(0)
	s_barrier
	ds_read_b128 v[18:21], v230
	ds_read_b128 v[86:89], v230 offset:512
	v_cvt_pk_bf16_f32 v158, v22, v23
	v_cvt_pk_bf16_f32 v159, v24, v25
	v_cvt_pk_bf16_f32 v160, v38, v39
	v_cvt_pk_bf16_f32 v161, v40, v41
	v_cvt_pk_bf16_f32 v150, v54, v55
	v_cvt_pk_bf16_f32 v151, v56, v57
	s_waitcnt lgkmcnt(1)
	v_mfma_f32_32x32x16_bf16 v[34:49], v[18:21], v[158:161], v[2:17]
	ds_read_b128 v[54:57], v230 offset:2560
	v_cvt_pk_bf16_f32 v152, v58, v59
	v_cvt_pk_bf16_f32 v153, v62, v63
	v_cvt_pk_bf16_f32 v142, v82, v69
	v_cvt_pk_bf16_f32 v145, v76, v71
	ds_read_b128 v[68:71], v230 offset:4608
	v_cvt_pk_bf16_f32 v143, v80, v73
	s_waitcnt lgkmcnt(2)
	v_mfma_f32_32x32x16_bf16 v[18:33], v[86:89], v[158:161], v[2:17]
	ds_read_b128 v[86:89], v230 offset:2048
	v_cvt_pk_bf16_f32 v144, v78, v75
	v_cvt_pk_bf16_f32 v134, v52, v53
	v_cvt_pk_bf16_f32 v135, v60, v61
	v_cvt_pk_bf16_f32 v136, v66, v67
	v_cvt_pk_bf16_f32 v137, v64, v65
	s_mov_b64 s[14:15], 0x6000
	s_waitcnt lgkmcnt(2)
	v_mfma_f32_32x32x16_bf16 v[18:33], v[54:57], v[150:153], v[18:33]
	ds_read_b128 v[54:57], v230 offset:4096
	s_add_i32 s5, s5, 0x8000
	v_lshlrev_b32_e32 v0, 1, v84
	v_and_b32_e32 v231, 32, v0
	v_lshlrev_b32_e32 v0, 3, v84
	v_lshlrev_b32_e32 v52, 4, v84
	v_and_b32_e32 v52, 0xc0, v52
	s_waitcnt lgkmcnt(1)
	v_mfma_f32_32x32x16_bf16 v[34:49], v[86:89], v[150:153], v[34:49]
	v_and_b32_e32 v232, 24, v0
	v_lshl_or_b32 v229, v228, 8, v52
	v_add_u32_e32 v52, 0, v231
	s_mov_b32 s10, 1
	v_add3_u32 v233, v52, v232, v229
	s_mov_b32 s4, 0
	s_movk_i32 s31, 0x4000
	s_waitcnt lgkmcnt(0)
	v_mfma_f32_32x32x16_bf16 v[34:49], v[54:57], v[142:145], v[34:49]
	ds_read_b128 v[54:57], v230 offset:6656
	ds_read_b128 v[72:75], v230 offset:6144
	s_cmp_lt_u32 s55, 7
	v_mfma_f32_32x32x16_bf16 v[18:33], v[68:71], v[142:145], v[18:33]
	s_waitcnt lgkmcnt(0)
	v_mfma_f32_32x32x16_bf16 v[34:49], v[72:75], v[134:137], v[34:49]
	v_mfma_f32_32x32x16_bf16 v[18:33], v[54:57], v[134:137], v[18:33]
	s_nop 15
	s_nop 7
	s_waitcnt vmcnt(0) lgkmcnt(0)
	s_barrier
	s_nop 10
	v_exp_f32_e32 v82, v34
	v_exp_f32_e32 v83, v35
	v_exp_f32_e32 v66, v18
	v_exp_f32_e32 v67, v19
	v_lshl_add_u64 v[18:19], v[194:195], 0, s[14:15]
	s_mov_b32 s6, m0
	s_mov_b32 m0, s18
	s_nop 0
	global_load_lds_dwordx4 v[18:19], off
	s_mov_b32 m0, s6
	s_mov_b64 s[6:7], 0x2000
	v_lshl_add_u64 v[196:197], v[50:51], 0, s[6:7]
	s_mov_b32 s6, m0
	s_mov_b32 m0, s5
	s_nop 0
	global_load_lds_dwordx4 v[196:197], off
	s_mov_b32 m0, s6
	ds_read_b128 v[190:193], v230 offset:8192
	ds_read_b128 v[186:189], v230 offset:8704
	ds_read_b128 v[182:185], v230 offset:10240
	ds_read_b128 v[178:181], v230 offset:10752
	ds_read_b128 v[174:177], v230 offset:12288
	ds_read_b128 v[170:173], v230 offset:12800
	ds_read_b128 v[166:169], v230 offset:14336
	ds_read_b128 v[162:165], v230 offset:14848
	v_exp_f32_e32 v84, v36
	v_exp_f32_e32 v85, v37
	v_exp_f32_e32 v86, v38
	v_exp_f32_e32 v87, v39
	v_exp_f32_e32 v88, v40
	v_exp_f32_e32 v89, v41
	v_exp_f32_e32 v90, v42
	v_exp_f32_e32 v91, v43
	v_exp_f32_e32 v92, v44
	v_exp_f32_e32 v93, v45
	v_exp_f32_e32 v94, v46
	v_exp_f32_e32 v95, v47
	v_exp_f32_e32 v96, v48
	v_exp_f32_e32 v97, v49
	v_exp_f32_e32 v68, v20
	v_exp_f32_e32 v69, v21
	v_exp_f32_e32 v70, v22
	v_exp_f32_e32 v71, v23
	v_exp_f32_e32 v72, v24
	v_exp_f32_e32 v73, v25
	v_exp_f32_e32 v74, v26
	v_exp_f32_e32 v75, v27
	v_exp_f32_e32 v76, v28
	v_exp_f32_e32 v77, v29
	v_exp_f32_e32 v78, v30
	v_exp_f32_e32 v79, v31
	v_exp_f32_e32 v80, v32
	v_exp_f32_e32 v81, v33
	s_waitcnt vmcnt(2) lgkmcnt(0)
	s_barrier
	s_cbranch_scc1 .LBB0_287
	v_lshl_add_u64 v[56:57], v[50:51], 0, s[14:15]
	s_mov_b64 s[4:5], 0xa000
	v_mov_b32_e32 v50, 0
	v_lshl_add_u64 v[58:59], v[194:195], 0, s[4:5]
	s_movk_i32 s30, 0x2000
	s_mov_b32 s7, 0
	s_mov_b32 s10, 6
	v_lshlrev_b32_e32 v240, 4, v224
	v_sub_u32_e32 v241, v58, v56
	v_readfirstlane_b32 s100, v56
	v_readfirstlane_b32 s101, v57
	v_add_u32_e32 v241, v241, v240
	s_nop 3
	s_sub_u32 s100, s100, 0x2000
	s_subb_u32 s101, s101, 0
	v_mov_b32_e32 v18, 0
	v_mov_b32_e32 v19, v50
	v_mov_b32_e32 v20, v50
	v_mov_b32_e32 v21, v50
	v_mov_b32_e32 v22, v50
	v_mov_b32_e32 v23, v50
	v_mov_b32_e32 v24, v50
	v_mov_b32_e32 v25, v50
	v_mov_b32_e32 v26, v50
	v_mov_b32_e32 v27, v50
	v_mov_b32_e32 v28, v50
	v_mov_b32_e32 v29, v50
	v_mov_b32_e32 v30, v50
	v_mov_b32_e32 v31, v50
	v_mov_b32_e32 v32, v50
	v_mov_b32_e32 v33, v50
	v_mov_b32_e32 v34, 0
	v_mov_b32_e32 v35, v50
	v_mov_b32_e32 v36, v50
	v_mov_b32_e32 v37, v50
	v_mov_b32_e32 v38, v50
	v_mov_b32_e32 v39, v50
	v_mov_b32_e32 v40, v50
	v_mov_b32_e32 v41, v50
	v_mov_b32_e32 v42, v50
	v_mov_b32_e32 v43, v50
	v_mov_b32_e32 v44, v50
	v_mov_b32_e32 v45, v50
	v_mov_b32_e32 v46, v50
	v_mov_b32_e32 v47, v50
	v_mov_b32_e32 v48, v50
	v_mov_b32_e32 v49, v50
	s_add_i32 s5, s10, 4
	s_cmp_lt_u32 s5, s55
	s_cbranch_scc0 .LBB0_278
.Lattn6:
	ds_read_b128 v[52:55], v240 offset:24576
	v_add_f32_e32 v60, v82, v83
	v_add_f32_e32 v60, v84, v60
	v_add_f32_e32 v60, v85, v60
	v_add_f32_e32 v60, v86, v60
	v_add_f32_e32 v64, v87, v60
	v_cvt_pk_bf16_f32 v154, v82, v83
	v_cvt_pk_bf16_f32 v155, v84, v85
	s_waitcnt lgkmcnt(9)
	v_mfma_f32_32x32x16_bf16 v[114:129], v[190:193], v[158:161], v[2:17]
	ds_read_b128 v[60:63], v240 offset:28672
	v_add_f32_e32 v64, v88, v64
	v_add_f32_e32 v64, v89, v64
	v_add_f32_e32 v64, v90, v64
	v_add_f32_e32 v64, v91, v64
	v_cvt_pk_bf16_f32 v156, v86, v87
	v_cvt_pk_bf16_f32 v157, v88, v89
	s_waitcnt lgkmcnt(10)
	v_mfma_f32_32x32x16_bf16 v[98:113], v[186:189], v[158:161], v[2:17]
	ds_read_b128 v[82:85], v240 offset:25600
	v_add_f32_e32 v64, v92, v64
	v_add_f32_e32 v64, v93, v64
	v_add_f32_e32 v64, v94, v64
	v_add_f32_e32 v64, v95, v64
	v_cvt_pk_bf16_f32 v146, v90, v91
	v_cvt_pk_bf16_f32 v147, v92, v93
	s_waitcnt lgkmcnt(11)
	v_mfma_f32_32x32x16_bf16 v[114:129], v[182:185], v[150:153], v[114:129]
	ds_read_b128 v[86:89], v240 offset:29696
	v_add_f32_e32 v64, v96, v64
	v_add_f32_e32 v64, v97, v64
	v_add_f32_e32 v64, v66, v64
	v_add_f32_e32 v64, v67, v64
	v_cvt_pk_bf16_f32 v148, v94, v95
	v_cvt_pk_bf16_f32 v149, v96, v97
	s_waitcnt lgkmcnt(12)
	v_mfma_f32_32x32x16_bf16 v[98:113], v[178:181], v[150:153], v[98:113]
	ds_read_b128 v[90:93], v240 offset:26624
	v_add_f32_e32 v64, v68, v64
	v_add_f32_e32 v64, v69, v64
	v_add_f32_e32 v64, v70, v64
	v_add_f32_e32 v94, v71, v64
	v_cvt_pk_bf16_f32 v138, v66, v67
	v_cvt_pk_bf16_f32 v139, v68, v69
	s_waitcnt lgkmcnt(13)
	v_mfma_f32_32x32x16_bf16 v[114:129], v[174:177], v[142:145], v[114:129]
	ds_read_b128 v[64:67], v240 offset:30720
	v_add_f32_e32 v68, v72, v94
	v_add_f32_e32 v68, v73, v68
	v_add_f32_e32 v68, v74, v68
	v_add_f32_e32 v94, v75, v68
	v_cvt_pk_bf16_f32 v140, v70, v71
	v_cvt_pk_bf16_f32 v141, v72, v73
	s_waitcnt lgkmcnt(14)
	v_mfma_f32_32x32x16_bf16 v[98:113], v[170:173], v[142:145], v[98:113]
	ds_read_b128 v[68:71], v240 offset:27648
	v_add_f32_e32 v72, v76, v94
	v_add_f32_e32 v72, v77, v72
	v_add_f32_e32 v72, v78, v72
	v_add_f32_e32 v94, v79, v72
	v_cvt_pk_bf16_f32 v130, v74, v75
	v_cvt_pk_bf16_f32 v131, v76, v77
	s_waitcnt lgkmcnt(14)
	v_mfma_f32_32x32x16_bf16 v[114:129], v[166:169], v[134:137], v[114:129]
	ds_read_b128 v[72:75], v240 offset:31744
	v_add_f32_e32 v51, v80, v94
	v_add_f32_e32 v51, v81, v51
	v_cvt_pk_bf16_f32 v132, v78, v79
	v_cvt_pk_bf16_f32 v133, v80, v81
	v_mfma_f32_32x32x16_bf16 v[98:113], v[162:165], v[134:137], v[98:113]
	s_add_i32 m0, s18, 0x2000
	s_nop 0
	global_load_lds_dwordx4 v241, s[100:101]
	s_add_i32 m0, s19, 0x4000
	s_nop 0
	global_load_lds_dwordx4 v240, s[100:101]
	s_waitcnt lgkmcnt(7)
	v_mfma_f32_32x32x16_bf16 v[18:33], v[154:157], v[52:55], v[18:33]
	s_add_u32 s100, s100, 0x2000
	s_addc_u32 s101, s101, 0
	v_exp_f32_e32 v114, v114
	v_exp_f32_e32 v115, v115
	v_exp_f32_e32 v116, v116
	v_exp_f32_e32 v117, v117
	s_waitcnt lgkmcnt(6)
	v_mfma_f32_32x32x16_bf16 v[34:49], v[154:157], v[60:63], v[34:49]
	v_exp_f32_e32 v118, v118
	v_exp_f32_e32 v119, v119
	v_exp_f32_e32 v120, v120
	v_exp_f32_e32 v121, v121
	ds_read_b128 v[60:63], v230 offset:16384
	ds_read_b128 v[162:165], v230 offset:16896
	s_waitcnt lgkmcnt(7)
	v_mfma_f32_32x32x16_bf16 v[18:33], v[146:149], v[82:85], v[18:33]
	v_exp_f32_e32 v122, v122
	v_exp_f32_e32 v123, v123
	v_exp_f32_e32 v124, v124
	v_exp_f32_e32 v125, v125
	ds_read_b128 v[166:169], v230 offset:18432
	ds_read_b128 v[170:173], v230 offset:18944
	s_waitcnt lgkmcnt(8)
	v_mfma_f32_32x32x16_bf16 v[34:49], v[146:149], v[86:89], v[34:49]
	v_exp_f32_e32 v126, v126
	v_exp_f32_e32 v127, v127
	v_exp_f32_e32 v128, v128
	v_exp_f32_e32 v129, v129
	ds_read_b128 v[174:177], v230 offset:20480
	ds_read_b128 v[178:181], v230 offset:20992
	s_waitcnt lgkmcnt(9)
	v_mfma_f32_32x32x16_bf16 v[18:33], v[138:141], v[90:93], v[18:33]
	v_exp_f32_e32 v98, v98
	v_exp_f32_e32 v99, v99
	v_exp_f32_e32 v100, v100
	v_exp_f32_e32 v101, v101
	ds_read_b128 v[182:185], v230 offset:22528
	ds_read_b128 v[52:55], v230 offset:23040
	s_waitcnt lgkmcnt(10)
	v_mfma_f32_32x32x16_bf16 v[34:49], v[138:141], v[64:67], v[34:49]
	v_exp_f32_e32 v102, v102
	v_exp_f32_e32 v103, v103
	v_exp_f32_e32 v104, v104
	v_exp_f32_e32 v105, v105
	s_waitcnt lgkmcnt(9)
	v_mfma_f32_32x32x16_bf16 v[18:33], v[130:133], v[68:71], v[18:33]
	v_exp_f32_e32 v106, v106
	v_exp_f32_e32 v107, v107
	v_exp_f32_e32 v108, v108
	v_exp_f32_e32 v109, v109
	s_waitcnt lgkmcnt(8)
	v_mfma_f32_32x32x16_bf16 v[34:49], v[130:133], v[72:75], v[34:49]
	v_exp_f32_e32 v110, v110
	v_exp_f32_e32 v111, v111
	v_exp_f32_e32 v112, v112
	v_exp_f32_e32 v113, v113
	s_waitcnt vmcnt(2) lgkmcnt(0)
	s_barrier
	ds_read_b128 v[186:189], v240 offset:32768
	s_waitcnt lgkmcnt(9)
	v_mfma_f32_32x32x16_bf16 v[82:97], v[60:63], v[158:161], v[2:17]
	v_add_f32_e32 v65, v114, v115
	v_add_f32_e32 v65, v116, v65
	v_add_f32_e32 v65, v117, v65
	v_add_f32_e32 v65, v118, v65
	v_add_f32_e32 v65, v119, v65
	v_cvt_pk_bf16_f32 v154, v114, v115
	v_cvt_pk_bf16_f32 v155, v116, v117
	ds_read_b128 v[60:63], v240 offset:36864
	s_waitcnt lgkmcnt(10)
	v_mfma_f32_32x32x16_bf16 v[66:81], v[162:165], v[158:161], v[2:17]
	v_add_f32_e32 v65, v120, v65
	v_add_f32_e32 v65, v121, v65
	v_add_f32_e32 v65, v122, v65
	v_add_f32_e32 v65, v123, v65
	v_cvt_pk_bf16_f32 v156, v118, v119
	v_cvt_pk_bf16_f32 v157, v120, v121
	ds_read_b128 v[114:117], v240 offset:33792
	s_waitcnt lgkmcnt(11)
	v_mfma_f32_32x32x16_bf16 v[82:97], v[166:169], v[150:153], v[82:97]
	v_add_f32_e32 v65, v124, v65
	v_add_f32_e32 v65, v125, v65
	v_add_f32_e32 v65, v126, v65
	v_add_f32_e32 v65, v127, v65
	v_cvt_pk_bf16_f32 v146, v122, v123
	v_cvt_pk_bf16_f32 v147, v124, v125
	ds_read_b128 v[118:121], v240 offset:37888
	s_waitcnt lgkmcnt(12)
	v_mfma_f32_32x32x16_bf16 v[66:81], v[170:173], v[150:153], v[66:81]
	v_add_f32_e32 v65, v128, v65
	v_add_f32_e32 v65, v129, v65
	v_add_f32_e32 v65, v98, v65
	v_add_f32_e32 v65, v99, v65
	v_cvt_pk_bf16_f32 v148, v126, v127
	v_cvt_pk_bf16_f32 v149, v128, v129
	ds_read_b128 v[122:125], v240 offset:34816
	s_waitcnt lgkmcnt(13)
	v_mfma_f32_32x32x16_bf16 v[82:97], v[174:177], v[142:145], v[82:97]
	v_add_f32_e32 v65, v100, v65
	v_add_f32_e32 v65, v101, v65
	v_add_f32_e32 v65, v102, v65
	v_add_f32_e32 v65, v103, v65
	v_cvt_pk_bf16_f32 v138, v98, v99
	v_cvt_pk_bf16_f32 v139, v100, v101
	ds_read_b128 v[98:101], v240 offset:38912
	s_waitcnt lgkmcnt(14)
	v_mfma_f32_32x32x16_bf16 v[66:81], v[178:181], v[142:145], v[66:81]
	v_add_f32_e32 v65, v104, v65
	v_add_f32_e32 v65, v105, v65
	v_add_f32_e32 v65, v106, v65
	v_add_f32_e32 v65, v107, v65
	v_cvt_pk_bf16_f32 v140, v102, v103
	v_cvt_pk_bf16_f32 v141, v104, v105
	ds_read_b128 v[102:105], v240 offset:35840
	s_waitcnt lgkmcnt(14)
	v_mfma_f32_32x32x16_bf16 v[82:97], v[182:185], v[134:137], v[82:97]
	v_add_f32_e32 v65, v108, v65
	v_add_f32_e32 v65, v109, v65
	v_add_f32_e32 v65, v110, v65
	v_add_f32_e32 v65, v111, v65
	v_cvt_pk_bf16_f32 v130, v106, v107
	v_cvt_pk_bf16_f32 v131, v108, v109
	ds_read_b128 v[106:109], v240 offset:39936
	v_mfma_f32_32x32x16_bf16 v[66:81], v[52:55], v[134:137], v[66:81]
	v_add_f32_e32 v52, v112, v65
	v_add_f32_e32 v52, v113, v52
	v_cvt_pk_bf16_f32 v132, v110, v111
	v_cvt_pk_bf16_f32 v133, v112, v113
	s_add_i32 m0, s18, 0x4000
	s_nop 0
	global_load_lds_dwordx4 v241, s[100:101]
	s_mov_b32 m0, s19
	s_nop 0
	global_load_lds_dwordx4 v240, s[100:101]
	s_waitcnt lgkmcnt(7)
	v_mfma_f32_32x32x16_bf16 v[18:33], v[154:157], v[186:189], v[18:33]
	s_add_u32 s100, s100, 0x2000
	s_addc_u32 s101, s101, 0
	v_exp_f32_e32 v82, v82
	v_exp_f32_e32 v83, v83
	v_exp_f32_e32 v84, v84
	v_exp_f32_e32 v85, v85
	s_waitcnt lgkmcnt(6)
	v_mfma_f32_32x32x16_bf16 v[34:49], v[154:157], v[60:63], v[34:49]
	v_exp_f32_e32 v86, v86
	v_exp_f32_e32 v87, v87
	v_exp_f32_e32 v88, v88
	v_exp_f32_e32 v89, v89
	ds_read_b128 v[190:193], v230
	ds_read_b128 v[186:189], v230 offset:512
	s_waitcnt lgkmcnt(7)
	v_mfma_f32_32x32x16_bf16 v[18:33], v[146:149], v[114:117], v[18:33]
	v_exp_f32_e32 v90, v90
	v_exp_f32_e32 v91, v91
	v_exp_f32_e32 v92, v92
	v_exp_f32_e32 v93, v93
	ds_read_b128 v[182:185], v230 offset:2048
	ds_read_b128 v[178:181], v230 offset:2560
	s_waitcnt lgkmcnt(8)
	v_mfma_f32_32x32x16_bf16 v[34:49], v[146:149], v[118:121], v[34:49]
	v_exp_f32_e32 v94, v94
	v_exp_f32_e32 v95, v95
	v_exp_f32_e32 v96, v96
	v_exp_f32_e32 v97, v97
	ds_read_b128 v[174:177], v230 offset:4096
	ds_read_b128 v[170:173], v230 offset:4608
	s_waitcnt lgkmcnt(9)
	v_mfma_f32_32x32x16_bf16 v[18:33], v[138:141], v[122:125], v[18:33]
	v_exp_f32_e32 v66, v66
	v_exp_f32_e32 v67, v67
	v_exp_f32_e32 v68, v68
	v_exp_f32_e32 v69, v69
	ds_read_b128 v[166:169], v230 offset:6144
	ds_read_b128 v[162:165], v230 offset:6656
	s_waitcnt lgkmcnt(10)
	v_mfma_f32_32x32x16_bf16 v[34:49], v[138:141], v[98:101], v[34:49]
	v_exp_f32_e32 v70, v70
	v_exp_f32_e32 v71, v71
	v_exp_f32_e32 v72, v72
	v_exp_f32_e32 v73, v73
	s_waitcnt lgkmcnt(9)
	v_mfma_f32_32x32x16_bf16 v[18:33], v[130:133], v[102:105], v[18:33]
	v_exp_f32_e32 v74, v74
	v_exp_f32_e32 v75, v75
	v_exp_f32_e32 v76, v76
	v_exp_f32_e32 v77, v77
	s_waitcnt lgkmcnt(8)
	v_mfma_f32_32x32x16_bf16 v[34:49], v[130:133], v[106:109], v[34:49]
	v_exp_f32_e32 v78, v78
	v_exp_f32_e32 v79, v79
	v_exp_f32_e32 v80, v80
	v_exp_f32_e32 v81, v81
	s_waitcnt vmcnt(2) lgkmcnt(0)
	s_barrier
	v_add_f32_e32 v50, v50, v51
	v_add_f32_e32 v50, v50, v52
	ds_read_b128 v[52:55], v240 offset:40960
	v_add_f32_e32 v60, v82, v83
	v_add_f32_e32 v60, v84, v60
	v_add_f32_e32 v60, v85, v60
	v_add_f32_e32 v60, v86, v60
	v_add_f32_e32 v64, v87, v60
	v_cvt_pk_bf16_f32 v154, v82, v83
	v_cvt_pk_bf16_f32 v155, v84, v85
	s_waitcnt lgkmcnt(9)
	v_mfma_f32_32x32x16_bf16 v[114:129], v[190:193], v[158:161], v[2:17]
	ds_read_b128 v[60:63], v240 offset:45056
	v_add_f32_e32 v64, v88, v64
	v_add_f32_e32 v64, v89, v64
	v_add_f32_e32 v64, v90, v64
	v_add_f32_e32 v64, v91, v64
	v_cvt_pk_bf16_f32 v156, v86, v87
	v_cvt_pk_bf16_f32 v157, v88, v89
	s_waitcnt lgkmcnt(10)
	v_mfma_f32_32x32x16_bf16 v[98:113], v[186:189], v[158:161], v[2:17]
	ds_read_b128 v[82:85], v240 offset:41984
	v_add_f32_e32 v64, v92, v64
	v_add_f32_e32 v64, v93, v64
	v_add_f32_e32 v64, v94, v64
	v_add_f32_e32 v64, v95, v64
	v_cvt_pk_bf16_f32 v146, v90, v91
	v_cvt_pk_bf16_f32 v147, v92, v93
	s_waitcnt lgkmcnt(11)
	v_mfma_f32_32x32x16_bf16 v[114:129], v[182:185], v[150:153], v[114:129]
	ds_read_b128 v[86:89], v240 offset:46080
	v_add_f32_e32 v64, v96, v64
	v_add_f32_e32 v64, v97, v64
	v_add_f32_e32 v64, v66, v64
	v_add_f32_e32 v64, v67, v64
	v_cvt_pk_bf16_f32 v148, v94, v95
	v_cvt_pk_bf16_f32 v149, v96, v97
	s_waitcnt lgkmcnt(12)
	v_mfma_f32_32x32x16_bf16 v[98:113], v[178:181], v[150:153], v[98:113]
	ds_read_b128 v[90:93], v240 offset:43008
	v_add_f32_e32 v64, v68, v64
	v_add_f32_e32 v64, v69, v64
	v_add_f32_e32 v64, v70, v64
	v_add_f32_e32 v94, v71, v64
	v_cvt_pk_bf16_f32 v138, v66, v67
	v_cvt_pk_bf16_f32 v139, v68, v69
	s_waitcnt lgkmcnt(13)
	v_mfma_f32_32x32x16_bf16 v[114:129], v[174:177], v[142:145], v[114:129]
	ds_read_b128 v[64:67], v240 offset:47104
	v_add_f32_e32 v68, v72, v94
	v_add_f32_e32 v68, v73, v68
	v_add_f32_e32 v68, v74, v68
	v_add_f32_e32 v94, v75, v68
	v_cvt_pk_bf16_f32 v140, v70, v71
	v_cvt_pk_bf16_f32 v141, v72, v73
	s_waitcnt lgkmcnt(14)
	v_mfma_f32_32x32x16_bf16 v[98:113], v[170:173], v[142:145], v[98:113]
	ds_read_b128 v[68:71], v240 offset:44032
	v_add_f32_e32 v72, v76, v94
	v_add_f32_e32 v72, v77, v72
	v_add_f32_e32 v72, v78, v72
	v_add_f32_e32 v94, v79, v72
	v_cvt_pk_bf16_f32 v130, v74, v75
	v_cvt_pk_bf16_f32 v131, v76, v77
	s_waitcnt lgkmcnt(14)
	v_mfma_f32_32x32x16_bf16 v[114:129], v[166:169], v[134:137], v[114:129]
	ds_read_b128 v[72:75], v240 offset:48128
	v_add_f32_e32 v51, v80, v94
	v_add_f32_e32 v51, v81, v51
	v_cvt_pk_bf16_f32 v132, v78, v79
	v_cvt_pk_bf16_f32 v133, v80, v81
	v_mfma_f32_32x32x16_bf16 v[98:113], v[162:165], v[134:137], v[98:113]
	s_mov_b32 m0, s18
	s_nop 0
	global_load_lds_dwordx4 v241, s[100:101]
	s_add_i32 m0, s19, 0x2000
	s_nop 0
	global_load_lds_dwordx4 v240, s[100:101]
	s_waitcnt lgkmcnt(7)
	v_mfma_f32_32x32x16_bf16 v[18:33], v[154:157], v[52:55], v[18:33]
	s_add_u32 s100, s100, 0x2000
	s_addc_u32 s101, s101, 0
	v_exp_f32_e32 v114, v114
	v_exp_f32_e32 v115, v115
	v_exp_f32_e32 v116, v116
	v_exp_f32_e32 v117, v117
	s_waitcnt lgkmcnt(6)
	v_mfma_f32_32x32x16_bf16 v[34:49], v[154:157], v[60:63], v[34:49]
	v_exp_f32_e32 v118, v118
	v_exp_f32_e32 v119, v119
	v_exp_f32_e32 v120, v120
	v_exp_f32_e32 v121, v121
	ds_read_b128 v[60:63], v230 offset:8192
	ds_read_b128 v[162:165], v230 offset:8704
	s_waitcnt lgkmcnt(7)
	v_mfma_f32_32x32x16_bf16 v[18:33], v[146:149], v[82:85], v[18:33]
	v_exp_f32_e32 v122, v122
	v_exp_f32_e32 v123, v123
	v_exp_f32_e32 v124, v124
	v_exp_f32_e32 v125, v125
	ds_read_b128 v[166:169], v230 offset:10240
	ds_read_b128 v[170:173], v230 offset:10752
	s_waitcnt lgkmcnt(8)
	v_mfma_f32_32x32x16_bf16 v[34:49], v[146:149], v[86:89], v[34:49]
	v_exp_f32_e32 v126, v126
	v_exp_f32_e32 v127, v127
	v_exp_f32_e32 v128, v128
	v_exp_f32_e32 v129, v129
	ds_read_b128 v[174:177], v230 offset:12288
	ds_read_b128 v[178:181], v230 offset:12800
	s_waitcnt lgkmcnt(9)
	v_mfma_f32_32x32x16_bf16 v[18:33], v[138:141], v[90:93], v[18:33]
	v_exp_f32_e32 v98, v98
	v_exp_f32_e32 v99, v99
	v_exp_f32_e32 v100, v100
	v_exp_f32_e32 v101, v101
	ds_read_b128 v[182:185], v230 offset:14336
	ds_read_b128 v[52:55], v230 offset:14848
	s_waitcnt lgkmcnt(10)
	v_mfma_f32_32x32x16_bf16 v[34:49], v[138:141], v[64:67], v[34:49]
	v_exp_f32_e32 v102, v102
	v_exp_f32_e32 v103, v103
	v_exp_f32_e32 v104, v104
	v_exp_f32_e32 v105, v105
	s_waitcnt lgkmcnt(9)
	v_mfma_f32_32x32x16_bf16 v[18:33], v[130:133], v[68:71], v[18:33]
	v_exp_f32_e32 v106, v106
	v_exp_f32_e32 v107, v107
	v_exp_f32_e32 v108, v108
	v_exp_f32_e32 v109, v109
	s_waitcnt lgkmcnt(8)
	v_mfma_f32_32x32x16_bf16 v[34:49], v[130:133], v[72:75], v[34:49]
	v_exp_f32_e32 v110, v110
	v_exp_f32_e32 v111, v111
	v_exp_f32_e32 v112, v112
	v_exp_f32_e32 v113, v113
	s_waitcnt vmcnt(2) lgkmcnt(0)
	s_barrier
	ds_read_b128 v[186:189], v240 offset:24576
	s_waitcnt lgkmcnt(9)
	v_mfma_f32_32x32x16_bf16 v[82:97], v[60:63], v[158:161], v[2:17]
	v_add_f32_e32 v65, v114, v115
	v_add_f32_e32 v65, v116, v65
	v_add_f32_e32 v65, v117, v65
	v_add_f32_e32 v65, v118, v65
	v_add_f32_e32 v65, v119, v65
	v_cvt_pk_bf16_f32 v154, v114, v115
	v_cvt_pk_bf16_f32 v155, v116, v117
	ds_read_b128 v[60:63], v240 offset:28672
	s_waitcnt lgkmcnt(10)
	v_mfma_f32_32x32x16_bf16 v[66:81], v[162:165], v[158:161], v[2:17]
	v_add_f32_e32 v65, v120, v65
	v_add_f32_e32 v65, v121, v65
	v_add_f32_e32 v65, v122, v65
	v_add_f32_e32 v65, v123, v65
	v_cvt_pk_bf16_f32 v156, v118, v119
	v_cvt_pk_bf16_f32 v157, v120, v121
	ds_read_b128 v[114:117], v240 offset:25600
	s_waitcnt lgkmcnt(11)
	v_mfma_f32_32x32x16_bf16 v[82:97], v[166:169], v[150:153], v[82:97]
	v_add_f32_e32 v65, v124, v65
	v_add_f32_e32 v65, v125, v65
	v_add_f32_e32 v65, v126, v65
	v_add_f32_e32 v65, v127, v65
	v_cvt_pk_bf16_f32 v146, v122, v123
	v_cvt_pk_bf16_f32 v147, v124, v125
	ds_read_b128 v[118:121], v240 offset:29696
	s_waitcnt lgkmcnt(12)
	v_mfma_f32_32x32x16_bf16 v[66:81], v[170:173], v[150:153], v[66:81]
	v_add_f32_e32 v65, v128, v65
	v_add_f32_e32 v65, v129, v65
	v_add_f32_e32 v65, v98, v65
	v_add_f32_e32 v65, v99, v65
	v_cvt_pk_bf16_f32 v148, v126, v127
	v_cvt_pk_bf16_f32 v149, v128, v129
	ds_read_b128 v[122:125], v240 offset:26624
	s_waitcnt lgkmcnt(13)
	v_mfma_f32_32x32x16_bf16 v[82:97], v[174:177], v[142:145], v[82:97]
	v_add_f32_e32 v65, v100, v65
	v_add_f32_e32 v65, v101, v65
	v_add_f32_e32 v65, v102, v65
	v_add_f32_e32 v65, v103, v65
	v_cvt_pk_bf16_f32 v138, v98, v99
	v_cvt_pk_bf16_f32 v139, v100, v101
	ds_read_b128 v[98:101], v240 offset:30720
	s_waitcnt lgkmcnt(14)
	v_mfma_f32_32x32x16_bf16 v[66:81], v[178:181], v[142:145], v[66:81]
	v_add_f32_e32 v65, v104, v65
	v_add_f32_e32 v65, v105, v65
	v_add_f32_e32 v65, v106, v65
	v_add_f32_e32 v65, v107, v65
	v_cvt_pk_bf16_f32 v140, v102, v103
	v_cvt_pk_bf16_f32 v141, v104, v105
	ds_read_b128 v[102:105], v240 offset:27648
	s_waitcnt lgkmcnt(14)
	v_mfma_f32_32x32x16_bf16 v[82:97], v[182:185], v[134:137], v[82:97]
	v_add_f32_e32 v65, v108, v65
	v_add_f32_e32 v65, v109, v65
	v_add_f32_e32 v65, v110, v65
	v_add_f32_e32 v65, v111, v65
	v_cvt_pk_bf16_f32 v130, v106, v107
	v_cvt_pk_bf16_f32 v131, v108, v109
	ds_read_b128 v[106:109], v240 offset:31744
	v_mfma_f32_32x32x16_bf16 v[66:81], v[52:55], v[134:137], v[66:81]
	v_add_f32_e32 v52, v112, v65
	v_add_f32_e32 v52, v113, v52
	v_cvt_pk_bf16_f32 v132, v110, v111
	v_cvt_pk_bf16_f32 v133, v112, v113
	s_add_i32 m0, s18, 0x2000
	s_nop 0
	global_load_lds_dwordx4 v241, s[100:101]
	s_add_i32 m0, s19, 0x4000
	s_nop 0
	global_load_lds_dwordx4 v240, s[100:101]
	s_waitcnt lgkmcnt(7)
	v_mfma_f32_32x32x16_bf16 v[18:33], v[154:157], v[186:189], v[18:33]
	s_add_u32 s100, s100, 0x2000
	s_addc_u32 s101, s101, 0
	v_exp_f32_e32 v82, v82
	v_exp_f32_e32 v83, v83
	v_exp_f32_e32 v84, v84
	v_exp_f32_e32 v85, v85
	s_waitcnt lgkmcnt(6)
	v_mfma_f32_32x32x16_bf16 v[34:49], v[154:157], v[60:63], v[34:49]
	v_exp_f32_e32 v86, v86
	v_exp_f32_e32 v87, v87
	v_exp_f32_e32 v88, v88
	v_exp_f32_e32 v89, v89
	ds_read_b128 v[190:193], v230 offset:16384
	ds_read_b128 v[186:189], v230 offset:16896
	s_waitcnt lgkmcnt(7)
	v_mfma_f32_32x32x16_bf16 v[18:33], v[146:149], v[114:117], v[18:33]
	v_exp_f32_e32 v90, v90
	v_exp_f32_e32 v91, v91
	v_exp_f32_e32 v92, v92
	v_exp_f32_e32 v93, v93
	ds_read_b128 v[182:185], v230 offset:18432
	ds_read_b128 v[178:181], v230 offset:18944
	s_waitcnt lgkmcnt(8)
	v_mfma_f32_32x32x16_bf16 v[34:49], v[146:149], v[118:121], v[34:49]
	v_exp_f32_e32 v94, v94
	v_exp_f32_e32 v95, v95
	v_exp_f32_e32 v96, v96
	v_exp_f32_e32 v97, v97
	ds_read_b128 v[174:177], v230 offset:20480
	ds_read_b128 v[170:173], v230 offset:20992
	s_waitcnt lgkmcnt(9)
	v_mfma_f32_32x32x16_bf16 v[18:33], v[138:141], v[122:125], v[18:33]
	v_exp_f32_e32 v66, v66
	v_exp_f32_e32 v67, v67
	v_exp_f32_e32 v68, v68
	v_exp_f32_e32 v69, v69
	ds_read_b128 v[166:169], v230 offset:22528
	ds_read_b128 v[162:165], v230 offset:23040
	s_waitcnt lgkmcnt(10)
	v_mfma_f32_32x32x16_bf16 v[34:49], v[138:141], v[98:101], v[34:49]
	v_exp_f32_e32 v70, v70
	v_exp_f32_e32 v71, v71
	v_exp_f32_e32 v72, v72
	v_exp_f32_e32 v73, v73
	s_waitcnt lgkmcnt(9)
	v_mfma_f32_32x32x16_bf16 v[18:33], v[130:133], v[102:105], v[18:33]
	v_exp_f32_e32 v74, v74
	v_exp_f32_e32 v75, v75
	v_exp_f32_e32 v76, v76
	v_exp_f32_e32 v77, v77
	s_waitcnt lgkmcnt(8)
	v_mfma_f32_32x32x16_bf16 v[34:49], v[130:133], v[106:109], v[34:49]
	v_exp_f32_e32 v78, v78
	v_exp_f32_e32 v79, v79
	v_exp_f32_e32 v80, v80
	v_exp_f32_e32 v81, v81
	s_waitcnt vmcnt(2) lgkmcnt(0)
	s_barrier
	v_add_f32_e32 v50, v50, v51
	v_add_f32_e32 v50, v50, v52
	ds_read_b128 v[52:55], v240 offset:32768
	v_add_f32_e32 v60, v82, v83
	v_add_f32_e32 v60, v84, v60
	v_add_f32_e32 v60, v85, v60
	v_add_f32_e32 v60, v86, v60
	v_add_f32_e32 v64, v87, v60
	v_cvt_pk_bf16_f32 v154, v82, v83
	v_cvt_pk_bf16_f32 v155, v84, v85
	s_waitcnt lgkmcnt(9)
	v_mfma_f32_32x32x16_bf16 v[114:129], v[190:193], v[158:161], v[2:17]
	ds_read_b128 v[60:63], v240 offset:36864
	v_add_f32_e32 v64, v88, v64
	v_add_f32_e32 v64, v89, v64
	v_add_f32_e32 v64, v90, v64
	v_add_f32_e32 v64, v91, v64
	v_cvt_pk_bf16_f32 v156, v86, v87
	v_cvt_pk_bf16_f32 v157, v88, v89
	s_waitcnt lgkmcnt(10)
	v_mfma_f32_32x32x16_bf16 v[98:113], v[186:189], v[158:161], v[2:17]
	ds_read_b128 v[82:85], v240 offset:33792
	v_add_f32_e32 v64, v92, v64
	v_add_f32_e32 v64, v93, v64
	v_add_f32_e32 v64, v94, v64
	v_add_f32_e32 v64, v95, v64
	v_cvt_pk_bf16_f32 v146, v90, v91
	v_cvt_pk_bf16_f32 v147, v92, v93
	s_waitcnt lgkmcnt(11)
	v_mfma_f32_32x32x16_bf16 v[114:129], v[182:185], v[150:153], v[114:129]
	ds_read_b128 v[86:89], v240 offset:37888
	v_add_f32_e32 v64, v96, v64
	v_add_f32_e32 v64, v97, v64
	v_add_f32_e32 v64, v66, v64
	v_add_f32_e32 v64, v67, v64
	v_cvt_pk_bf16_f32 v148, v94, v95
	v_cvt_pk_bf16_f32 v149, v96, v97
	s_waitcnt lgkmcnt(12)
	v_mfma_f32_32x32x16_bf16 v[98:113], v[178:181], v[150:153], v[98:113]
	ds_read_b128 v[90:93], v240 offset:34816
	v_add_f32_e32 v64, v68, v64
	v_add_f32_e32 v64, v69, v64
	v_add_f32_e32 v64, v70, v64
	v_add_f32_e32 v94, v71, v64
	v_cvt_pk_bf16_f32 v138, v66, v67
	v_cvt_pk_bf16_f32 v139, v68, v69
	s_waitcnt lgkmcnt(13)
	v_mfma_f32_32x32x16_bf16 v[114:129], v[174:177], v[142:145], v[114:129]
	ds_read_b128 v[64:67], v240 offset:38912
	v_add_f32_e32 v68, v72, v94
	v_add_f32_e32 v68, v73, v68
	v_add_f32_e32 v68, v74, v68
	v_add_f32_e32 v94, v75, v68
	v_cvt_pk_bf16_f32 v140, v70, v71
	v_cvt_pk_bf16_f32 v141, v72, v73
	s_waitcnt lgkmcnt(14)
	v_mfma_f32_32x32x16_bf16 v[98:113], v[170:173], v[142:145], v[98:113]
	ds_read_b128 v[68:71], v240 offset:35840
	v_add_f32_e32 v72, v76, v94
	v_add_f32_e32 v72, v77, v72
	v_add_f32_e32 v72, v78, v72
	v_add_f32_e32 v94, v79, v72
	v_cvt_pk_bf16_f32 v130, v74, v75
	v_cvt_pk_bf16_f32 v131, v76, v77
	s_waitcnt lgkmcnt(14)
	v_mfma_f32_32x32x16_bf16 v[114:129], v[166:169], v[134:137], v[114:129]
	ds_read_b128 v[72:75], v240 offset:39936
	v_add_f32_e32 v51, v80, v94
	v_add_f32_e32 v51, v81, v51
	v_cvt_pk_bf16_f32 v132, v78, v79
	v_cvt_pk_bf16_f32 v133, v80, v81
	v_mfma_f32_32x32x16_bf16 v[98:113], v[162:165], v[134:137], v[98:113]
	s_add_i32 m0, s18, 0x4000
	s_nop 0
	global_load_lds_dwordx4 v241, s[100:101]
	s_mov_b32 m0, s19
	s_nop 0
	global_load_lds_dwordx4 v240, s[100:101]
	s_waitcnt lgkmcnt(7)
	v_mfma_f32_32x32x16_bf16 v[18:33], v[154:157], v[52:55], v[18:33]
	s_add_u32 s100, s100, 0x2000
	s_addc_u32 s101, s101, 0
	v_exp_f32_e32 v114, v114
	v_exp_f32_e32 v115, v115
	v_exp_f32_e32 v116, v116
	v_exp_f32_e32 v117, v117
	s_waitcnt lgkmcnt(6)
	v_mfma_f32_32x32x16_bf16 v[34:49], v[154:157], v[60:63], v[34:49]
	v_exp_f32_e32 v118, v118
	v_exp_f32_e32 v119, v119
	v_exp_f32_e32 v120, v120
	v_exp_f32_e32 v121, v121
	ds_read_b128 v[60:63], v230
	ds_read_b128 v[162:165], v230 offset:512
	s_waitcnt lgkmcnt(7)
	v_mfma_f32_32x32x16_bf16 v[18:33], v[146:149], v[82:85], v[18:33]
	v_exp_f32_e32 v122, v122
	v_exp_f32_e32 v123, v123
	v_exp_f32_e32 v124, v124
	v_exp_f32_e32 v125, v125
	ds_read_b128 v[166:169], v230 offset:2048
	ds_read_b128 v[170:173], v230 offset:2560
	s_waitcnt lgkmcnt(8)
	v_mfma_f32_32x32x16_bf16 v[34:49], v[146:149], v[86:89], v[34:49]
	v_exp_f32_e32 v126, v126
	v_exp_f32_e32 v127, v127
	v_exp_f32_e32 v128, v128
	v_exp_f32_e32 v129, v129
	ds_read_b128 v[174:177], v230 offset:4096
	ds_read_b128 v[178:181], v230 offset:4608
	s_waitcnt lgkmcnt(9)
	v_mfma_f32_32x32x16_bf16 v[18:33], v[138:141], v[90:93], v[18:33]
	v_exp_f32_e32 v98, v98
	v_exp_f32_e32 v99, v99
	v_exp_f32_e32 v100, v100
	v_exp_f32_e32 v101, v101
	ds_read_b128 v[182:185], v230 offset:6144
	ds_read_b128 v[52:55], v230 offset:6656
	s_waitcnt lgkmcnt(10)
	v_mfma_f32_32x32x16_bf16 v[34:49], v[138:141], v[64:67], v[34:49]
	v_exp_f32_e32 v102, v102
	v_exp_f32_e32 v103, v103
	v_exp_f32_e32 v104, v104
	v_exp_f32_e32 v105, v105
	s_waitcnt lgkmcnt(9)
	v_mfma_f32_32x32x16_bf16 v[18:33], v[130:133], v[68:71], v[18:33]
	v_exp_f32_e32 v106, v106
	v_exp_f32_e32 v107, v107
	v_exp_f32_e32 v108, v108
	v_exp_f32_e32 v109, v109
	s_waitcnt lgkmcnt(8)
	v_mfma_f32_32x32x16_bf16 v[34:49], v[130:133], v[72:75], v[34:49]
	v_exp_f32_e32 v110, v110
	v_exp_f32_e32 v111, v111
	v_exp_f32_e32 v112, v112
	v_exp_f32_e32 v113, v113
	s_waitcnt vmcnt(2) lgkmcnt(0)
	s_barrier
; #define WAIT_BAR(N) asm volatile("s_waitcnt vmcnt(" #N ") lgkmcnt(0)\n\ts_barrier":::"memory")
;   #define RESC() do{ if(resc){ asm volatile("s_waitcnt lgkmcnt(0)":::"memory"); \
;       _Pragma("unroll") for(int d_=0;d_<2;++d_) _Pragma("unroll") for(int r=0;r<16;++r)o[d_][r]*=wsf[crow(r,hi)]; } }while(0)
;   #define ROT() do{sl_prev=sl_cur;sl_cur=sl_next;sl_next=(sl_next==(NSLOT-1)*SLOTB)?0:sl_next+SLOTB;}while(0)
; template<int THRL,bool FIXREF> __device__ __forceinline__ void attn_unit(const float*gq,const float*tab,const int tq0,const bf16*Qw0,const bf16*__restrict__ Kl,const bf16*__restrict__ Vl,const int NT,bf16*Ow0,char*shm){
;     ...
;   int t=1;
;     ...
;   for(;t+5<NT;t+=2){
;     STEP(pB0,pB1,pA0,pA1,t,true,true,true);     WAIT_BAR(2); RESC(); ROT();
;     STEP(pA0,pA1,pB0,pB1,t+1,true,true,true);   WAIT_BAR(2); RESC(); ROT();
;   }
	ds_read_b128 v[186:189], v240 offset:40960
	s_waitcnt lgkmcnt(9)
	v_mfma_f32_32x32x16_bf16 v[82:97], v[60:63], v[158:161], v[2:17]
	v_add_f32_e32 v65, v114, v115
	v_add_f32_e32 v65, v116, v65
	v_add_f32_e32 v65, v117, v65
	v_add_f32_e32 v65, v118, v65
	v_add_f32_e32 v65, v119, v65
	v_cvt_pk_bf16_f32 v154, v114, v115
	v_cvt_pk_bf16_f32 v155, v116, v117
	ds_read_b128 v[60:63], v240 offset:45056
	s_waitcnt lgkmcnt(10)
	v_mfma_f32_32x32x16_bf16 v[66:81], v[162:165], v[158:161], v[2:17]
	v_add_f32_e32 v65, v120, v65
	v_add_f32_e32 v65, v121, v65
	v_add_f32_e32 v65, v122, v65
	v_add_f32_e32 v65, v123, v65
	v_cvt_pk_bf16_f32 v156, v118, v119
	v_cvt_pk_bf16_f32 v157, v120, v121
	ds_read_b128 v[114:117], v240 offset:41984
	s_waitcnt lgkmcnt(11)
	v_mfma_f32_32x32x16_bf16 v[82:97], v[166:169], v[150:153], v[82:97]
	v_add_f32_e32 v65, v124, v65
	v_add_f32_e32 v65, v125, v65
	v_add_f32_e32 v65, v126, v65
	v_add_f32_e32 v65, v127, v65
	v_cvt_pk_bf16_f32 v146, v122, v123
	v_cvt_pk_bf16_f32 v147, v124, v125
	ds_read_b128 v[118:121], v240 offset:46080
	s_waitcnt lgkmcnt(12)
	v_mfma_f32_32x32x16_bf16 v[66:81], v[170:173], v[150:153], v[66:81]
	v_add_f32_e32 v65, v128, v65
	v_add_f32_e32 v65, v129, v65
	v_add_f32_e32 v65, v98, v65
	v_add_f32_e32 v65, v99, v65
	v_cvt_pk_bf16_f32 v148, v126, v127
	v_cvt_pk_bf16_f32 v149, v128, v129
	ds_read_b128 v[122:125], v240 offset:43008
	s_waitcnt lgkmcnt(13)
	v_mfma_f32_32x32x16_bf16 v[82:97], v[174:177], v[142:145], v[82:97]
	v_add_f32_e32 v65, v100, v65
	v_add_f32_e32 v65, v101, v65
	v_add_f32_e32 v65, v102, v65
	v_add_f32_e32 v65, v103, v65
	v_cvt_pk_bf16_f32 v138, v98, v99
	v_cvt_pk_bf16_f32 v139, v100, v101
	ds_read_b128 v[98:101], v240 offset:47104
	s_waitcnt lgkmcnt(14)
	v_mfma_f32_32x32x16_bf16 v[66:81], v[178:181], v[142:145], v[66:81]
	v_add_f32_e32 v65, v104, v65
	v_add_f32_e32 v65, v105, v65
	v_add_f32_e32 v65, v106, v65
	v_add_f32_e32 v65, v107, v65
	v_cvt_pk_bf16_f32 v140, v102, v103
	v_cvt_pk_bf16_f32 v141, v104, v105
	ds_read_b128 v[102:105], v240 offset:44032
	s_waitcnt lgkmcnt(14)
	v_mfma_f32_32x32x16_bf16 v[82:97], v[182:185], v[134:137], v[82:97]
	v_add_f32_e32 v65, v108, v65
	v_add_f32_e32 v65, v109, v65
	v_add_f32_e32 v65, v110, v65
	v_add_f32_e32 v65, v111, v65
	v_cvt_pk_bf16_f32 v130, v106, v107
	v_cvt_pk_bf16_f32 v131, v108, v109
	ds_read_b128 v[106:109], v240 offset:48128
	v_mfma_f32_32x32x16_bf16 v[66:81], v[52:55], v[134:137], v[66:81]
	v_add_f32_e32 v52, v112, v65
	v_add_f32_e32 v52, v113, v52
	v_cvt_pk_bf16_f32 v132, v110, v111
	v_cvt_pk_bf16_f32 v133, v112, v113
	s_mov_b32 m0, s18
	s_nop 0
	global_load_lds_dwordx4 v241, s[100:101]
	s_add_i32 m0, s19, 0x2000
	s_nop 0
	global_load_lds_dwordx4 v240, s[100:101]
	s_waitcnt lgkmcnt(7)
	v_mfma_f32_32x32x16_bf16 v[18:33], v[154:157], v[186:189], v[18:33]
	s_add_u32 s100, s100, 0x2000
	s_addc_u32 s101, s101, 0
	v_exp_f32_e32 v82, v82
	v_exp_f32_e32 v83, v83
	v_exp_f32_e32 v84, v84
	v_exp_f32_e32 v85, v85
	s_waitcnt lgkmcnt(6)
	v_mfma_f32_32x32x16_bf16 v[34:49], v[154:157], v[60:63], v[34:49]
	v_exp_f32_e32 v86, v86
	v_exp_f32_e32 v87, v87
	v_exp_f32_e32 v88, v88
	v_exp_f32_e32 v89, v89
	ds_read_b128 v[190:193], v230 offset:8192
	ds_read_b128 v[186:189], v230 offset:8704
	s_waitcnt lgkmcnt(7)
	v_mfma_f32_32x32x16_bf16 v[18:33], v[146:149], v[114:117], v[18:33]
	v_exp_f32_e32 v90, v90
	v_exp_f32_e32 v91, v91
	v_exp_f32_e32 v92, v92
	v_exp_f32_e32 v93, v93
	ds_read_b128 v[182:185], v230 offset:10240
	ds_read_b128 v[178:181], v230 offset:10752
	s_waitcnt lgkmcnt(8)
	v_mfma_f32_32x32x16_bf16 v[34:49], v[146:149], v[118:121], v[34:49]
	v_exp_f32_e32 v94, v94
	v_exp_f32_e32 v95, v95
	v_exp_f32_e32 v96, v96
	v_exp_f32_e32 v97, v97
	ds_read_b128 v[174:177], v230 offset:12288
	ds_read_b128 v[170:173], v230 offset:12800
	s_waitcnt lgkmcnt(9)
	v_mfma_f32_32x32x16_bf16 v[18:33], v[138:141], v[122:125], v[18:33]
	v_exp_f32_e32 v66, v66
	v_exp_f32_e32 v67, v67
	v_exp_f32_e32 v68, v68
	v_exp_f32_e32 v69, v69
	ds_read_b128 v[166:169], v230 offset:14336
	ds_read_b128 v[162:165], v230 offset:14848
	s_waitcnt lgkmcnt(10)
	v_mfma_f32_32x32x16_bf16 v[34:49], v[138:141], v[98:101], v[34:49]
	v_exp_f32_e32 v70, v70
	v_exp_f32_e32 v71, v71
	v_exp_f32_e32 v72, v72
	v_exp_f32_e32 v73, v73
	s_waitcnt lgkmcnt(9)
	v_mfma_f32_32x32x16_bf16 v[18:33], v[130:133], v[102:105], v[18:33]
	v_exp_f32_e32 v74, v74
	v_exp_f32_e32 v75, v75
	v_exp_f32_e32 v76, v76
	v_exp_f32_e32 v77, v77
	s_waitcnt lgkmcnt(8)
	v_mfma_f32_32x32x16_bf16 v[34:49], v[130:133], v[106:109], v[34:49]
	v_exp_f32_e32 v78, v78
	v_exp_f32_e32 v79, v79
	v_exp_f32_e32 v80, v80
	v_exp_f32_e32 v81, v81
	s_waitcnt vmcnt(2) lgkmcnt(0)
	s_barrier
	v_add_f32_e32 v50, v50, v51
	v_add_f32_e32 v50, v50, v52
	s_add_i32 s10, s10, 6
	s_add_i32 s5, s10, 4
	s_cmp_lt_u32 s5, s55
	s_cbranch_scc1 .Lattn6
	s_cmp_lt_u32 s10, s55
	s_cbranch_scc1 .LBB0_278
	s_mov_b32 s4, 0
	s_add_i32 s5, s10, -2
	s_branch .Lattn6_exit
;   #define RESC() do{ if(resc){ asm volatile("s_waitcnt lgkmcnt(0)":::"memory"); \
;       _Pragma("unroll") for(int d_=0;d_<2;++d_) _Pragma("unroll") for(int r=0;r<16;++r)o[d_][r]*=wsf[crow(r,hi)]; } }while(0)
;   #define ROT() do{sl_prev=sl_cur;sl_cur=sl_next;sl_next=(sl_next==(NSLOT-1)*SLOTB)?0:sl_next+SLOTB;}while(0)
;   #define ENDW(tt) do{ if((tt)+3<NT){WAIT_BAR(2);} else if((tt)+2<NT){WAIT_BAR(1);} else {WAIT_BAR(0);} }while(0)
; template<int THRL,bool FIXREF> __device__ __forceinline__ void attn_unit(const float*gq,const float*tab,const int tq0,const bf16*Qw0,const bf16*__restrict__ Kl,const bf16*__restrict__ Vl,const int NT,bf16*Ow0,char*shm){
;     ...
;   for(;t+1<NT;t+=2){
;     STEP(pB0,pB1,pA0,pA1,t,(t+3<NT),(t+1<NT),(t+1<NT));       ENDW(t);   RESC(); ROT();
;     STEP(pA0,pA1,pB0,pB1,t+1,(t+4<NT),(t+2<NT),(t+2<NT));     ENDW(t+1); RESC(); ROT();
;   }
.LBB0_278:
	s_mov_b32 s4, s31
	s_mov_b32 s5, s10
	s_mov_b32 s6, s30
	v_add_u32_e32 v51, s7, v240
	ds_read_b128 v[52:55], v51 offset:24576
	ds_read_b32 v242, v240 offset:0
	v_add_f32_e32 v60, v82, v83
	v_add_f32_e32 v60, v84, v60
	v_add_f32_e32 v60, v85, v60
	v_add_f32_e32 v60, v86, v60
	v_add_f32_e32 v64, v87, v60
	v_cvt_pk_bf16_f32 v154, v82, v83
	v_cvt_pk_bf16_f32 v155, v84, v85
	s_waitcnt lgkmcnt(9)
	v_mfma_f32_32x32x16_bf16 v[114:129], v[190:193], v[158:161], v[2:17]
	ds_read_b128 v[60:63], v51 offset:28672
	ds_read_b32 v242, v240 offset:4096
	v_add_f32_e32 v64, v88, v64
	v_add_f32_e32 v64, v89, v64
	v_add_f32_e32 v64, v90, v64
	v_add_f32_e32 v64, v91, v64
	v_cvt_pk_bf16_f32 v156, v86, v87
	v_cvt_pk_bf16_f32 v157, v88, v89
	s_waitcnt lgkmcnt(10)
	v_mfma_f32_32x32x16_bf16 v[98:113], v[186:189], v[158:161], v[2:17]
	ds_read_b128 v[82:85], v51 offset:25600
	ds_read_b32 v242, v240 offset:1024
	v_add_f32_e32 v64, v92, v64
	v_add_f32_e32 v64, v93, v64
	v_add_f32_e32 v64, v94, v64
	v_add_f32_e32 v64, v95, v64
	v_cvt_pk_bf16_f32 v146, v90, v91
	v_cvt_pk_bf16_f32 v147, v92, v93
	s_waitcnt lgkmcnt(11)
	v_mfma_f32_32x32x16_bf16 v[114:129], v[182:185], v[150:153], v[114:129]
	ds_read_b128 v[86:89], v51 offset:29696
	ds_read_b32 v242, v240 offset:5120
	v_add_f32_e32 v64, v96, v64
	v_add_f32_e32 v64, v97, v64
	v_add_f32_e32 v64, v66, v64
	v_add_f32_e32 v64, v67, v64
	v_cvt_pk_bf16_f32 v148, v94, v95
	v_cvt_pk_bf16_f32 v149, v96, v97
	s_waitcnt lgkmcnt(12)
	v_mfma_f32_32x32x16_bf16 v[98:113], v[178:181], v[150:153], v[98:113]
	ds_read_b128 v[90:93], v51 offset:26624
	ds_read_b32 v242, v240 offset:2048
	v_add_f32_e32 v64, v68, v64
	v_add_f32_e32 v64, v69, v64
	v_add_f32_e32 v64, v70, v64
	v_add_f32_e32 v94, v71, v64
	v_cvt_pk_bf16_f32 v138, v66, v67
	v_cvt_pk_bf16_f32 v139, v68, v69
	s_waitcnt lgkmcnt(13)
	v_mfma_f32_32x32x16_bf16 v[114:129], v[174:177], v[142:145], v[114:129]
	ds_read_b128 v[64:67], v51 offset:30720
	ds_read_b32 v242, v240 offset:6144
	v_add_f32_e32 v68, v72, v94
	v_add_f32_e32 v68, v73, v68
	v_add_f32_e32 v68, v74, v68
	v_add_f32_e32 v94, v75, v68
	v_cvt_pk_bf16_f32 v140, v70, v71
	v_cvt_pk_bf16_f32 v141, v72, v73
	s_waitcnt lgkmcnt(14)
	v_mfma_f32_32x32x16_bf16 v[98:113], v[170:173], v[142:145], v[98:113]
	ds_read_b128 v[68:71], v51 offset:27648
	ds_read_b32 v242, v240 offset:3072
	v_add_f32_e32 v72, v76, v94
	v_add_f32_e32 v72, v77, v72
	v_add_f32_e32 v72, v78, v72
	v_add_f32_e32 v94, v79, v72
	v_cvt_pk_bf16_f32 v130, v74, v75
	v_cvt_pk_bf16_f32 v131, v76, v77
	s_waitcnt lgkmcnt(14)
	v_mfma_f32_32x32x16_bf16 v[114:129], v[166:169], v[134:137], v[114:129]
	ds_read_b128 v[72:75], v51 offset:31744
	ds_read_b32 v242, v240 offset:7168
	v_add_f32_e32 v51, v80, v94
	v_add_f32_e32 v51, v81, v51
	v_add_f32_e32 v51, 0, v51
	v_cvt_pk_bf16_f32 v132, v78, v79
	v_cvt_pk_bf16_f32 v133, v80, v81
	v_mfma_f32_32x32x16_bf16 v[98:113], v[162:165], v[134:137], v[98:113]
	s_add_i32 m0, s30, s18
	s_nop 0
	global_load_lds_dwordx4 v241, s[100:101]
	s_add_i32 m0, s31, s19
	s_nop 0
	global_load_lds_dwordx4 v240, s[100:101]
	s_waitcnt lgkmcnt(14)
	v_mfma_f32_32x32x16_bf16 v[18:33], v[154:157], v[52:55], v[18:33]
	s_add_u32 s100, s100, 0x2000
	s_addc_u32 s101, s101, 0
	v_exp_f32_e32 v114, v114
	v_exp_f32_e32 v115, v115
	v_exp_f32_e32 v116, v116
	v_exp_f32_e32 v117, v117
	s_waitcnt lgkmcnt(12)
	v_mfma_f32_32x32x16_bf16 v[34:49], v[154:157], v[60:63], v[34:49]
	v_exp_f32_e32 v118, v118
	v_exp_f32_e32 v119, v119
	v_exp_f32_e32 v120, v120
	v_exp_f32_e32 v121, v121
	v_add_u32_e32 v52, s4, v230
	ds_read_b128 v[60:63], v52
	ds_read_b128 v[162:165], v52 offset:512
	s_waitcnt lgkmcnt(12)
	v_mfma_f32_32x32x16_bf16 v[18:33], v[146:149], v[82:85], v[18:33]
	v_exp_f32_e32 v122, v122
	v_exp_f32_e32 v123, v123
	v_exp_f32_e32 v124, v124
	v_exp_f32_e32 v125, v125
	ds_read_b128 v[166:169], v52 offset:2048
	ds_read_b128 v[170:173], v52 offset:2560
	s_waitcnt lgkmcnt(12)
	v_mfma_f32_32x32x16_bf16 v[34:49], v[146:149], v[86:89], v[34:49]
	v_exp_f32_e32 v126, v126
	v_exp_f32_e32 v127, v127
	v_exp_f32_e32 v128, v128
	v_exp_f32_e32 v129, v129
	ds_read_b128 v[174:177], v52 offset:4096
	ds_read_b128 v[178:181], v52 offset:4608
	s_waitcnt lgkmcnt(12)
	v_mfma_f32_32x32x16_bf16 v[18:33], v[138:141], v[90:93], v[18:33]
	v_exp_f32_e32 v98, v98
	v_exp_f32_e32 v99, v99
	v_exp_f32_e32 v100, v100
	v_exp_f32_e32 v101, v101
	ds_read_b128 v[182:185], v52 offset:6144
	ds_read_b128 v[52:55], v52 offset:6656
	s_waitcnt lgkmcnt(12)
	v_mfma_f32_32x32x16_bf16 v[34:49], v[138:141], v[64:67], v[34:49]
	v_exp_f32_e32 v102, v102
	v_exp_f32_e32 v103, v103
	v_exp_f32_e32 v104, v104
	v_exp_f32_e32 v105, v105
	s_waitcnt lgkmcnt(10)
	v_mfma_f32_32x32x16_bf16 v[18:33], v[130:133], v[68:71], v[18:33]
	v_exp_f32_e32 v106, v106
	v_exp_f32_e32 v107, v107
	v_exp_f32_e32 v108, v108
	v_exp_f32_e32 v109, v109
	s_waitcnt lgkmcnt(8)
	v_mfma_f32_32x32x16_bf16 v[34:49], v[130:133], v[72:75], v[34:49]
	v_exp_f32_e32 v110, v110
	v_exp_f32_e32 v111, v111
	v_exp_f32_e32 v112, v112
	v_exp_f32_e32 v113, v113
	s_waitcnt vmcnt(2) lgkmcnt(0)
	s_barrier
;   #define RESC() do{ if(resc){ asm volatile("s_waitcnt lgkmcnt(0)":::"memory"); \
;       _Pragma("unroll") for(int d_=0;d_<2;++d_) _Pragma("unroll") for(int r=0;r<16;++r)o[d_][r]*=wsf[crow(r,hi)]; } }while(0)
;   #define ROT() do{sl_prev=sl_cur;sl_cur=sl_next;sl_next=(sl_next==(NSLOT-1)*SLOTB)?0:sl_next+SLOTB;}while(0)
;   #define ENDW(tt) do{ if((tt)+3<NT){WAIT_BAR(2);} else if((tt)+2<NT){WAIT_BAR(1);} else {WAIT_BAR(0);} }while(0)
; template<int THRL,bool FIXREF> __device__ __forceinline__ void attn_unit(const float*gq,const float*tab,const int tq0,const bf16*Qw0,const bf16*__restrict__ Kl,const bf16*__restrict__ Vl,const int NT,bf16*Ow0,char*shm){
;     ...
;   for(;t+1<NT;t+=2){
;     STEP(pB0,pB1,pA0,pA1,t,(t+3<NT),(t+1<NT),(t+1<NT));       ENDW(t);   RESC(); ROT();
;     STEP(pA0,pA1,pB0,pB1,t+1,(t+4<NT),(t+2<NT),(t+2<NT));     ENDW(t+1); RESC(); ROT();
;   }
	s_add_i32 s7, s31, 0x2000
	s_cmpk_lg_i32 s31, 0x4000
	s_cselect_b32 s30, s7, 0
	v_add_u32_e32 v64, s6, v240
	ds_read_b128 v[186:189], v64 offset:24576
	ds_read_b32 v242, v240 offset:0
	s_waitcnt lgkmcnt(9)
	v_mfma_f32_32x32x16_bf16 v[82:97], v[60:63], v[158:161], v[2:17]
	v_add_f32_e32 v65, v114, v115
	v_add_f32_e32 v65, v116, v65
	v_add_f32_e32 v65, v117, v65
	v_add_f32_e32 v65, v118, v65
	v_add_f32_e32 v65, v119, v65
	v_cvt_pk_bf16_f32 v154, v114, v115
	v_cvt_pk_bf16_f32 v155, v116, v117
	ds_read_b128 v[60:63], v64 offset:28672
	ds_read_b32 v242, v240 offset:4096
	s_waitcnt lgkmcnt(10)
	v_mfma_f32_32x32x16_bf16 v[66:81], v[162:165], v[158:161], v[2:17]
	v_add_f32_e32 v65, v120, v65
	v_add_f32_e32 v65, v121, v65
	v_add_f32_e32 v65, v122, v65
	v_add_f32_e32 v65, v123, v65
	v_cvt_pk_bf16_f32 v156, v118, v119
	v_cvt_pk_bf16_f32 v157, v120, v121
	ds_read_b128 v[114:117], v64 offset:25600
	ds_read_b32 v242, v240 offset:1024
	s_waitcnt lgkmcnt(11)
	v_mfma_f32_32x32x16_bf16 v[82:97], v[166:169], v[150:153], v[82:97]
	v_add_f32_e32 v65, v124, v65
	v_add_f32_e32 v65, v125, v65
	v_add_f32_e32 v65, v126, v65
	v_add_f32_e32 v65, v127, v65
	v_cvt_pk_bf16_f32 v146, v122, v123
	v_cvt_pk_bf16_f32 v147, v124, v125
	ds_read_b128 v[118:121], v64 offset:29696
	ds_read_b32 v242, v240 offset:5120
	s_waitcnt lgkmcnt(12)
	v_mfma_f32_32x32x16_bf16 v[66:81], v[170:173], v[150:153], v[66:81]
	v_add_f32_e32 v65, v128, v65
	v_add_f32_e32 v65, v129, v65
	v_add_f32_e32 v65, v98, v65
	v_add_f32_e32 v65, v99, v65
	v_cvt_pk_bf16_f32 v148, v126, v127
	v_cvt_pk_bf16_f32 v149, v128, v129
	ds_read_b128 v[122:125], v64 offset:26624
	ds_read_b32 v242, v240 offset:2048
	s_waitcnt lgkmcnt(13)
	v_mfma_f32_32x32x16_bf16 v[82:97], v[174:177], v[142:145], v[82:97]
	v_add_f32_e32 v65, v100, v65
	v_add_f32_e32 v65, v101, v65
	v_add_f32_e32 v65, v102, v65
	v_add_f32_e32 v65, v103, v65
	v_cvt_pk_bf16_f32 v138, v98, v99
	v_cvt_pk_bf16_f32 v139, v100, v101
	ds_read_b128 v[98:101], v64 offset:30720
	ds_read_b32 v242, v240 offset:6144
	s_waitcnt lgkmcnt(14)
	v_mfma_f32_32x32x16_bf16 v[66:81], v[178:181], v[142:145], v[66:81]
	v_add_f32_e32 v65, v104, v65
	v_add_f32_e32 v65, v105, v65
	v_add_f32_e32 v65, v106, v65
	v_add_f32_e32 v65, v107, v65
	v_cvt_pk_bf16_f32 v140, v102, v103
	v_cvt_pk_bf16_f32 v141, v104, v105
	ds_read_b128 v[102:105], v64 offset:27648
	ds_read_b32 v242, v240 offset:3072
	s_waitcnt lgkmcnt(14)
	v_mfma_f32_32x32x16_bf16 v[82:97], v[182:185], v[134:137], v[82:97]
	v_add_f32_e32 v65, v108, v65
	v_add_f32_e32 v65, v109, v65
	v_add_f32_e32 v65, v110, v65
	v_add_f32_e32 v65, v111, v65
	v_cvt_pk_bf16_f32 v130, v106, v107
	v_cvt_pk_bf16_f32 v131, v108, v109
	ds_read_b128 v[106:109], v64 offset:31744
	ds_read_b32 v242, v240 offset:7168
	v_mfma_f32_32x32x16_bf16 v[66:81], v[52:55], v[134:137], v[66:81]
	v_add_f32_e32 v52, v112, v65
	v_add_f32_e32 v52, v113, v52
	v_add_f32_e32 v52, 0, v52
	v_cvt_pk_bf16_f32 v132, v110, v111
	v_cvt_pk_bf16_f32 v133, v112, v113
	s_add_i32 m0, s31, s18
	s_nop 0
	global_load_lds_dwordx4 v241, s[100:101]
	s_add_i32 m0, s30, s19
	s_nop 0
	global_load_lds_dwordx4 v240, s[100:101]
	s_waitcnt lgkmcnt(14)
	v_mfma_f32_32x32x16_bf16 v[18:33], v[154:157], v[186:189], v[18:33]
	s_add_u32 s100, s100, 0x2000
	s_addc_u32 s101, s101, 0
	v_exp_f32_e32 v82, v82
	v_exp_f32_e32 v83, v83
	v_exp_f32_e32 v84, v84
	v_exp_f32_e32 v85, v85
	s_waitcnt lgkmcnt(12)
	v_mfma_f32_32x32x16_bf16 v[34:49], v[154:157], v[60:63], v[34:49]
	v_exp_f32_e32 v86, v86
	v_exp_f32_e32 v87, v87
	v_exp_f32_e32 v88, v88
	v_exp_f32_e32 v89, v89
	v_add_u32_e32 v53, s30, v230
	ds_read_b128 v[190:193], v53
	ds_read_b128 v[186:189], v53 offset:512
	s_waitcnt lgkmcnt(12)
	v_mfma_f32_32x32x16_bf16 v[18:33], v[146:149], v[114:117], v[18:33]
	v_exp_f32_e32 v90, v90
	v_exp_f32_e32 v91, v91
	v_exp_f32_e32 v92, v92
	v_exp_f32_e32 v93, v93
	ds_read_b128 v[182:185], v53 offset:2048
	ds_read_b128 v[178:181], v53 offset:2560
	s_waitcnt lgkmcnt(12)
	v_mfma_f32_32x32x16_bf16 v[34:49], v[146:149], v[118:121], v[34:49]
	v_exp_f32_e32 v94, v94
	v_exp_f32_e32 v95, v95
	v_exp_f32_e32 v96, v96
	v_exp_f32_e32 v97, v97
	ds_read_b128 v[174:177], v53 offset:4096
	ds_read_b128 v[170:173], v53 offset:4608
	s_waitcnt lgkmcnt(12)
	v_mfma_f32_32x32x16_bf16 v[18:33], v[138:141], v[122:125], v[18:33]
	v_exp_f32_e32 v66, v66
	v_exp_f32_e32 v67, v67
	v_exp_f32_e32 v68, v68
	v_exp_f32_e32 v69, v69
	ds_read_b128 v[166:169], v53 offset:6144
	ds_read_b128 v[162:165], v53 offset:6656
	s_waitcnt lgkmcnt(12)
	v_mfma_f32_32x32x16_bf16 v[34:49], v[138:141], v[98:101], v[34:49]
	v_exp_f32_e32 v70, v70
	v_exp_f32_e32 v71, v71
	v_exp_f32_e32 v72, v72
	v_exp_f32_e32 v73, v73
	s_waitcnt lgkmcnt(10)
	v_mfma_f32_32x32x16_bf16 v[18:33], v[130:133], v[102:105], v[18:33]
	v_exp_f32_e32 v74, v74
	v_exp_f32_e32 v75, v75
	v_exp_f32_e32 v76, v76
	v_exp_f32_e32 v77, v77
	s_waitcnt lgkmcnt(8)
	v_mfma_f32_32x32x16_bf16 v[34:49], v[130:133], v[106:109], v[34:49]
	v_exp_f32_e32 v78, v78
	v_exp_f32_e32 v79, v79
	v_exp_f32_e32 v80, v80
	v_exp_f32_e32 v81, v81
	s_add_i32 s6, s30, 0x2000
	s_waitcnt vmcnt(2) lgkmcnt(0)
	s_barrier
	s_cmpk_lg_i32 s30, 0x4000
	v_add_f32_e32 v50, v50, v51
	s_mov_b32 s7, s31
	s_cselect_b32 s31, s6, 0
	s_add_i32 s10, s5, 2
	s_cmp_ge_u32 s10, s55
	v_add_f32_e32 v50, v50, v52
	s_cbranch_scc0 .LBB0_278

; #define SBAR() __builtin_amdgcn_sched_barrier(0)
;   #define RESC() do{ if(resc){ asm volatile("s_waitcnt lgkmcnt(0)":::"memory"); \
;       _Pragma("unroll") for(int d_=0;d_<2;++d_) _Pragma("unroll") for(int r=0;r<16;++r)o[d_][r]*=wsf[crow(r,hi)]; } }while(0)
;   #define PKW(P,B) cvtpk_s(P[B],P[B+1])
; template<int THRL,bool FIXREF> __device__ __forceinline__ void attn_unit(const float*gq,const float*tab,const int tq0,const bf16*Qw0,const bf16*__restrict__ Kl,const bf16*__restrict__ Vl,const int NT,bf16*Ow0,char*shm){
;     ...
;   STEP(pB0,pB1,pA0,pA1,NT-1,false,false,false); RESC();
;   { float sacc=pB0[0]+pB0[1]; _Pragma("unroll") for(int r=2;r<16;++r)sacc+=pB0[r]; _Pragma("unroll") for(int r=0;r<16;++r)sacc+=pB1[r]; l_reg+=sacc;
;     pw0=(u32x4){PKW(pB0,0),PKW(pB0,2),PKW(pB0,4),PKW(pB0,6)};pw1=(u32x4){PKW(pB0,8),PKW(pB0,10),PKW(pB0,12),PKW(pB0,14)};pw2=(u32x4){PKW(pB1,0),PKW(pB1,2),PKW(pB1,4),PKW(pB1,6)};pw3=(u32x4){PKW(pB1,8),PKW(pB1,10),PKW(pB1,12),PKW(pB1,14)};
;     SBAR(); pv(o,vb0+sl_cur,PAF(0),PAF(1),PAF(2),PAF(3)); }
.LBB0_281:
	s_and_b32 s4, s29, 0x3fffffc0
	s_cmp_lg_u32 0, -1
	s_cselect_b32 s5, 0, 0
	s_lshl_b32 s4, s4, 2
	s_addk_i32 s5, 0x6000
	s_add_i32 s6, s4, 0
	v_add3_u32 v51, v231, s5, v232
	v_add_u32_e32 v114, s31, v240
	ds_read_b128 v[52:55], v114 offset:24576
	ds_read_b32 v242, v240 offset:0
	v_add_f32_e32 v56, v82, v83
	v_add_f32_e32 v56, v84, v56
	v_add_f32_e32 v56, v85, v56
	v_add_f32_e32 v56, v86, v56
	v_add_f32_e32 v60, v87, v56
	v_cvt_pk_bf16_f32 v154, v82, v83
	v_cvt_pk_bf16_f32 v155, v84, v85
	s_waitcnt lgkmcnt(9)
	v_mfma_f32_32x32x16_bf16 v[98:113], v[190:193], v[158:161], v[2:17]
	ds_read_b128 v[56:59], v114 offset:28672
	ds_read_b32 v242, v240 offset:4096
	s_waitcnt lgkmcnt(10)
	v_mfma_f32_32x32x16_bf16 v[2:17], v[186:189], v[158:161], v[2:17]
	v_add_f32_e32 v60, v88, v60
	v_add_f32_e32 v60, v89, v60
	v_add_f32_e32 v60, v90, v60
	v_add_f32_e32 v64, v91, v60
	v_cvt_pk_bf16_f32 v156, v86, v87
	v_cvt_pk_bf16_f32 v157, v88, v89
	ds_read_b128 v[60:63], v114 offset:25600
	ds_read_b32 v242, v240 offset:1024
	v_add_f32_e32 v64, v92, v64
	v_add_f32_e32 v64, v93, v64
	v_add_f32_e32 v64, v94, v64
	v_add_f32_e32 v64, v95, v64
	v_cvt_pk_bf16_f32 v146, v90, v91
	v_cvt_pk_bf16_f32 v147, v92, v93
	s_waitcnt lgkmcnt(11)
	v_mfma_f32_32x32x16_bf16 v[98:113], v[182:185], v[150:153], v[98:113]
	ds_read_b128 v[82:85], v114 offset:29696
	ds_read_b32 v242, v240 offset:5120
	s_waitcnt lgkmcnt(12)
	v_mfma_f32_32x32x16_bf16 v[2:17], v[178:181], v[150:153], v[2:17]
	v_add_f32_e32 v64, v96, v64
	v_add_f32_e32 v64, v97, v64
	v_add_f32_e32 v64, v66, v64
	v_add_f32_e32 v64, v67, v64
	v_cvt_pk_bf16_f32 v148, v94, v95
	v_cvt_pk_bf16_f32 v149, v96, v97
	ds_read_b128 v[86:89], v114 offset:26624
	ds_read_b32 v242, v240 offset:2048
	v_add_f32_e32 v64, v68, v64
	v_add_f32_e32 v64, v69, v64
	v_add_f32_e32 v64, v70, v64
	v_add_f32_e32 v90, v71, v64
	v_cvt_pk_bf16_f32 v138, v66, v67
	v_cvt_pk_bf16_f32 v139, v68, v69
	s_waitcnt lgkmcnt(13)
	v_mfma_f32_32x32x16_bf16 v[98:113], v[174:177], v[142:145], v[98:113]
	ds_read_b128 v[64:67], v114 offset:30720
	ds_read_b32 v242, v240 offset:6144
	s_waitcnt lgkmcnt(14)
	v_mfma_f32_32x32x16_bf16 v[2:17], v[170:173], v[142:145], v[2:17]
	v_add_f32_e32 v68, v72, v90
	v_add_f32_e32 v68, v73, v68
	v_add_f32_e32 v68, v74, v68
	v_add_f32_e32 v90, v75, v68
	v_cvt_pk_bf16_f32 v140, v70, v71
	v_cvt_pk_bf16_f32 v141, v72, v73
	ds_read_b128 v[68:71], v114 offset:27648
	ds_read_b32 v242, v240 offset:3072
	v_add_f32_e32 v72, v76, v90
	v_add_f32_e32 v72, v77, v72
	v_add_f32_e32 v72, v78, v72
	v_add_f32_e32 v90, v79, v72
	v_cvt_pk_bf16_f32 v130, v74, v75
	v_cvt_pk_bf16_f32 v131, v76, v77
	s_waitcnt lgkmcnt(14)
	v_mfma_f32_32x32x16_bf16 v[98:113], v[166:169], v[134:137], v[98:113]
	ds_read_b128 v[72:75], v114 offset:31744
	ds_read_b32 v242, v240 offset:7168
	v_mfma_f32_32x32x16_bf16 v[2:17], v[162:165], v[134:137], v[2:17]
	v_add_f32_e32 v76, v80, v90
	v_add_f32_e32 v76, v81, v76
	v_add_f32_e32 v76, 0, v76
	v_cvt_pk_bf16_f32 v132, v78, v79
	v_cvt_pk_bf16_f32 v133, v80, v81
	s_waitcnt lgkmcnt(14)
	v_mfma_f32_32x32x16_bf16 v[18:33], v[154:157], v[52:55], v[18:33]
	s_nop 1
	v_exp_f32_e32 v98, v98
	v_exp_f32_e32 v99, v99
	v_exp_f32_e32 v100, v100
	v_exp_f32_e32 v101, v101
	s_waitcnt lgkmcnt(12)
	v_mfma_f32_32x32x16_bf16 v[34:49], v[154:157], v[56:59], v[34:49]
	v_exp_f32_e32 v102, v102
	v_exp_f32_e32 v103, v103
	v_exp_f32_e32 v104, v104
	v_exp_f32_e32 v105, v105
	s_waitcnt lgkmcnt(10)
	v_mfma_f32_32x32x16_bf16 v[18:33], v[146:149], v[60:63], v[18:33]
	v_exp_f32_e32 v106, v106
	v_exp_f32_e32 v107, v107
	v_exp_f32_e32 v108, v108
	v_exp_f32_e32 v109, v109
	s_waitcnt lgkmcnt(8)
	v_mfma_f32_32x32x16_bf16 v[34:49], v[146:149], v[82:85], v[34:49]
	v_exp_f32_e32 v110, v110
	v_exp_f32_e32 v111, v111
	v_exp_f32_e32 v112, v112
	v_exp_f32_e32 v113, v113
	s_waitcnt lgkmcnt(6)
	v_mfma_f32_32x32x16_bf16 v[18:33], v[138:141], v[86:89], v[18:33]
	v_exp_f32_e32 v2, v2
	v_exp_f32_e32 v3, v3
	v_exp_f32_e32 v4, v4
	v_exp_f32_e32 v5, v5
	s_waitcnt lgkmcnt(4)
	v_mfma_f32_32x32x16_bf16 v[34:49], v[138:141], v[64:67], v[34:49]
	v_exp_f32_e32 v6, v6
	v_exp_f32_e32 v7, v7
	v_exp_f32_e32 v8, v8
	v_exp_f32_e32 v9, v9
	s_waitcnt lgkmcnt(2)
	v_mfma_f32_32x32x16_bf16 v[18:33], v[130:133], v[68:71], v[18:33]
	v_exp_f32_e32 v10, v10
	v_exp_f32_e32 v11, v11
	v_exp_f32_e32 v12, v12
	v_exp_f32_e32 v13, v13
	s_waitcnt lgkmcnt(0)
	v_mfma_f32_32x32x16_bf16 v[34:49], v[130:133], v[72:75], v[34:49]
	v_exp_f32_e32 v14, v14
	v_exp_f32_e32 v15, v15
	v_exp_f32_e32 v16, v16
	v_exp_f32_e32 v17, v17
	v_add_f32_e32 v52, v98, v99
	v_add_f32_e32 v52, v100, v52
	v_add_f32_e32 v52, v101, v52
	v_add_f32_e32 v52, v102, v52
	v_add_f32_e32 v52, v103, v52
	v_add_f32_e32 v52, v104, v52
	v_add_f32_e32 v52, v105, v52
	v_add_f32_e32 v52, v106, v52
	v_add_f32_e32 v52, v107, v52
	v_add_f32_e32 v52, v108, v52
	v_add_f32_e32 v52, v109, v52
	v_add_f32_e32 v52, v110, v52
	v_add_f32_e32 v52, v111, v52
	v_add_f32_e32 v52, v112, v52
	v_add_f32_e32 v52, v113, v52
	v_add_f32_e32 v52, v2, v52
	v_add_f32_e32 v52, v3, v52
	v_add_f32_e32 v52, v4, v52
	v_add_f32_e32 v52, v5, v52
	v_add_f32_e32 v52, v6, v52
	v_add_f32_e32 v52, v7, v52
	v_add_f32_e32 v52, v8, v52
	v_add_f32_e32 v52, v9, v52
	v_add_f32_e32 v52, v10, v52
	v_add_f32_e32 v52, v11, v52
	v_add_f32_e32 v52, v12, v52
	v_add_f32_e32 v52, v13, v52
	v_add_f32_e32 v52, v14, v52
	v_add_f32_e32 v52, v15, v52
	v_add_f32_e32 v52, v16, v52
	v_add_f32_e32 v52, v17, v52
	v_add_f32_e32 v50, v50, v76
	v_add_f32_e32 v50, v50, v52
	v_cvt_pk_bf16_f32 v2, v2, v3
	v_cvt_pk_bf16_f32 v52, v98, v99
	v_cvt_pk_bf16_f32 v53, v100, v101
	v_cvt_pk_bf16_f32 v54, v102, v103
	v_cvt_pk_bf16_f32 v55, v104, v105
	v_cvt_pk_bf16_f32 v56, v106, v107
	v_cvt_pk_bf16_f32 v57, v108, v109
	v_cvt_pk_bf16_f32 v58, v110, v111
	v_cvt_pk_bf16_f32 v59, v112, v113
	v_cvt_pk_bf16_f32 v3, v4, v5
	v_cvt_pk_bf16_f32 v4, v6, v7
	v_cvt_pk_bf16_f32 v5, v8, v9
	v_cvt_pk_bf16_f32 v6, v10, v11
	v_cvt_pk_bf16_f32 v7, v12, v13
	v_cvt_pk_bf16_f32 v8, v14, v15
	v_cvt_pk_bf16_f32 v9, v16, v17
	v_add_u32_e32 v51, s30, v240
	v_add_u32_e32 v51, 0x6000, v51
	ds_read_b128 v[10:13], v51 offset:0
	ds_read_b32 v242, v240 offset:0
	ds_read_b128 v[14:17], v51 offset:1024
	ds_read_b32 v242, v240 offset:1024
	ds_read_b128 v[60:63], v51 offset:2048
	ds_read_b32 v242, v240 offset:2048
	ds_read_b128 v[64:67], v51 offset:3072
	ds_read_b32 v242, v240 offset:3072
	s_waitcnt lgkmcnt(0)
; __device__ __forceinline__ int crow(int r,int hi){return (r&3)+8*(r>>2)+4*hi;}
; #define SBAR() __builtin_amdgcn_sched_barrier(0)
; __device__ __forceinline__ void pv(f32x16*o,int vb,bf16x8 pa0,bf16x8 pa1,bf16x8 pa2,bf16x8 pa3){
;   #pragma unroll
;   for(int d0=0;d0<2;++d0){s16x4 lo[4],hi[4];
;     #pragma unroll
;     for(int ks=0;ks<4;++ks){
;       asm volatile("ds_read_b64_tr_b16 %0,%1 offset:%c2":"=&v"(lo[ks]):"v"(vb),"i"(d0*4096+ks*1024):"memory");
;       asm volatile("ds_read_b64_tr_b16 %0,%1 offset:%c2":"=&v"(hi[ks]):"v"(vb),"i"(d0*4096+ks*1024+512):"memory");}
;     asm volatile("s_waitcnt lgkmcnt(0)":::"memory");SBAR();
;     ...
;     o[d0]=__builtin_amdgcn_mfma_f32_32x32x16_bf16(pa0,PK(0),o[d0],0,0,0);
;     o[d0]=__builtin_amdgcn_mfma_f32_32x32x16_bf16(pa1,PK(1),o[d0],0,0,0);
;     o[d0]=__builtin_amdgcn_mfma_f32_32x32x16_bf16(pa2,PK(2),o[d0],0,0,0);
;     o[d0]=__builtin_amdgcn_mfma_f32_32x32x16_bf16(pa3,PK(3),o[d0],0,0,0);
;     ...
;   }
; }
; template<int THRL,bool FIXREF> __device__ __forceinline__ void attn_unit(const float*gq,const float*tab,const int tq0,const bf16*Qw0,const bf16*__restrict__ Kl,const bf16*__restrict__ Vl,const int NT,bf16*Ow0,char*shm){
;     ...
;   {auto rr=__builtin_amdgcn_permlane32_swap(__float_as_uint(l_reg),__float_as_uint(l_reg),false,false);l_reg=__uint_as_float(rr[0])+__uint_as_float(rr[1]);}
;   if(hi==0)wsf[32+r32]=l_reg;asm volatile("s_waitcnt lgkmcnt(0)":::"memory");
;   float rli[16];
;   #pragma unroll
;   for(int r=0;r<16;++r)rli[r]=__builtin_amdgcn_rcpf(wsf[32+crow(r,hi)]);
;   bf16*Ow=Ow0+(long)(wid*QBLK)*OP;
;   { bf16*stg=(bf16*)(shm+LDS_OST)+wid*2048;
;     #pragma unroll
;     for(int r=0;r<16;++r){const int orow=crow(r,hi);
;       #pragma unroll
;       for(int d0=0;d0<2;++d0)stg[orow*64+d0*32+r32]=__float2bfloat16(o[d0][r]*rli[r]);}
;     asm volatile("s_waitcnt lgkmcnt(0)":::"memory");
;     #pragma unroll
;     for(int i=0;i<4;++i){const int row=i*8+(lane>>3),ch=lane&7; const u32x4 v=*(const u32x4*)(stg+row*64+ch*8); ATTN_STORE16(Ow+(long)row*OP+ch*8,v);} }
;   asm volatile("s_waitcnt lgkmcnt(0)\n\ts_barrier":::"memory");
	s_nop 0
	v_mfma_f32_32x32x16_bf16 v[18:33], v[52:55], v[10:13], v[18:33]
	ds_read_b128 v[10:13], v51 offset:4096
	ds_read_b32 v242, v240 offset:4096
	v_mfma_f32_32x32x16_bf16 v[18:33], v[56:59], v[14:17], v[18:33]
	ds_read_b128 v[14:17], v51 offset:5120
	ds_read_b32 v242, v240 offset:5120
	v_mfma_f32_32x32x16_bf16 v[18:33], v[2:5], v[60:63], v[18:33]
	ds_read_b128 v[60:63], v51 offset:6144
	ds_read_b32 v242, v240 offset:6144
	v_mfma_f32_32x32x16_bf16 v[18:33], v[6:9], v[64:67], v[18:33]
	ds_read_b128 v[64:67], v51 offset:7168
	ds_read_b32 v242, v240 offset:7168
	s_waitcnt lgkmcnt(0)
	v_mfma_f32_32x32x16_bf16 v[34:49], v[52:55], v[10:13], v[34:49]
	v_cmp_gt_u32_e32 vcc, 32, v226
	v_mfma_f32_32x32x16_bf16 v[34:49], v[56:59], v[14:17], v[34:49]
	v_mfma_f32_32x32x16_bf16 v[34:49], v[2:5], v[60:63], v[34:49]
	v_mov_b32_e32 v2, v50
	s_nop 1
	v_permlane32_swap_b32_e32 v50, v2
	v_mfma_f32_32x32x16_bf16 v[34:49], v[6:9], v[64:67], v[34:49]
	s_and_saveexec_b64 s[4:5], vcc
	v_add_f32_e32 v2, v50, v2
	v_lshl_add_u32 v3, v227, 2, s6
	ds_write_b32 v3, v2 offset:49280
	s_or_b64 exec, exec, s[4:5]
	s_waitcnt lgkmcnt(0)
	v_lshl_add_u32 v10, v228, 4, s6
	ds_read_b128 v[2:5], v10 offset:49280
	ds_read_b128 v[6:9], v10 offset:49312
	s_lshl_b32 s6, s28, 12
	s_add_i32 s6, s6, 0
	v_lshlrev_b32_e32 v51, 1, v227
	s_waitcnt lgkmcnt(1)
	v_rcp_f32_e32 v11, v2
	v_rcp_f32_e32 v12, v3
	v_rcp_f32_e32 v13, v4
	v_rcp_f32_e32 v14, v5
	s_waitcnt lgkmcnt(0)
	v_rcp_f32_e32 v15, v6
	ds_read_b128 v[2:5], v10 offset:49344
	v_rcp_f32_e32 v16, v7
	v_rcp_f32_e32 v17, v8
	v_rcp_f32_e32 v50, v9
	ds_read_b128 v[6:9], v10 offset:49376
	v_lshlrev_b32_e32 v10, 9, v228
	v_mul_f32_e32 v18, v18, v11
	v_mul_f32_e32 v11, v34, v11
	v_add3_u32 v10, s6, v10, v51
	v_cvt_pk_bf16_f32 v11, v11, s0
	ds_write_b16 v10, v11 offset:51264
	v_mul_f32_e32 v11, v19, v12
	v_cvt_pk_bf16_f32 v11, v11, s0
	ds_write_b16 v10, v11 offset:51328
	v_mul_f32_e32 v11, v35, v12
	v_cvt_pk_bf16_f32 v11, v11, s0
	ds_write_b16 v10, v11 offset:51392
	v_mul_f32_e32 v11, v20, v13
	v_cvt_pk_bf16_f32 v11, v11, s0
	ds_write_b16 v10, v11 offset:51456
	v_mul_f32_e32 v11, v36, v13
	v_cvt_pk_bf16_f32 v11, v11, s0
	ds_write_b16 v10, v11 offset:51520
	v_mul_f32_e32 v11, v21, v14
	v_cvt_pk_bf16_f32 v11, v11, s0
	ds_write_b16 v10, v11 offset:51584
	v_mul_f32_e32 v11, v37, v14
	v_cvt_pk_bf16_f32 v11, v11, s0
	ds_write_b16 v10, v11 offset:51648
	v_mul_f32_e32 v11, v22, v15
	v_cvt_pk_bf16_f32 v11, v11, s0
	ds_write_b16 v10, v11 offset:52224
	v_mul_f32_e32 v11, v38, v15
	v_cvt_pk_bf16_f32 v11, v11, s0
	ds_write_b16 v10, v11 offset:52288
	v_mul_f32_e32 v11, v23, v16
	v_cvt_pk_bf16_f32 v11, v11, s0
	ds_write_b16 v10, v11 offset:52352
	v_mul_f32_e32 v11, v39, v16
	v_cvt_pk_bf16_f32 v11, v11, s0
	ds_write_b16 v10, v11 offset:52416
	v_mul_f32_e32 v11, v24, v17
	v_cvt_pk_bf16_f32 v11, v11, s0
	ds_write_b16 v10, v11 offset:52480
	v_mul_f32_e32 v11, v40, v17
	v_cvt_pk_bf16_f32 v11, v11, s0
	s_waitcnt lgkmcnt(13)
	v_rcp_f32_e32 v2, v2
	ds_write_b16 v10, v11 offset:52544
	v_mul_f32_e32 v11, v25, v50
	v_cvt_pk_bf16_f32 v11, v11, s0
	v_rcp_f32_e32 v3, v3
	ds_write_b16 v10, v11 offset:52608
	v_mul_f32_e32 v11, v41, v50
	v_cvt_pk_bf16_f32 v11, v11, s0
	ds_write_b16 v10, v11 offset:52672
	v_mul_f32_e32 v11, v26, v2
	v_mul_f32_e32 v2, v42, v2
	v_cvt_pk_bf16_f32 v2, v2, s0
	v_rcp_f32_e32 v4, v4
	ds_write_b16 v10, v2 offset:53312
	v_mul_f32_e32 v2, v27, v3
	v_cvt_pk_bf16_f32 v2, v2, s0
	ds_write_b16 v10, v2 offset:53376
	v_mul_f32_e32 v2, v43, v3
	v_cvt_pk_bf16_f32 v2, v2, s0
	v_rcp_f32_e32 v5, v5
	ds_write_b16 v10, v2 offset:53440
	v_mul_f32_e32 v2, v28, v4
	v_cvt_pk_bf16_f32 v2, v2, s0
	ds_write_b16 v10, v2 offset:53504
	v_mul_f32_e32 v2, v44, v4
	v_cvt_pk_bf16_f32 v2, v2, s0
	s_waitcnt lgkmcnt(14)
	v_rcp_f32_e32 v6, v6
	ds_write_b16 v10, v2 offset:53568
	v_mul_f32_e32 v2, v29, v5
	v_cvt_pk_bf16_f32 v2, v2, s0
	ds_write_b16 v10, v2 offset:53632
	v_mul_f32_e32 v2, v45, v5
	v_cvt_pk_bf16_f32 v2, v2, s0
	v_rcp_f32_e32 v7, v7
	ds_write_b16 v10, v2 offset:53696
	v_mul_f32_e32 v2, v30, v6
	v_cvt_pk_bf16_f32 v2, v2, s0
	ds_write_b16 v10, v2 offset:54272
	v_mul_f32_e32 v2, v46, v6
	v_cvt_pk_bf16_f32 v2, v2, s0
	v_rcp_f32_e32 v8, v8
	ds_write_b16 v10, v2 offset:54336
	v_mul_f32_e32 v2, v31, v7
	v_cvt_pk_bf16_f32 v2, v2, s0
	ds_write_b16 v10, v2 offset:54400
	v_mul_f32_e32 v2, v47, v7
	v_cvt_pk_bf16_f32 v2, v2, s0
	v_rcp_f32_e32 v9, v9
	ds_write_b16 v10, v2 offset:54464
	v_mul_f32_e32 v2, v32, v8
	v_cvt_pk_bf16_f32 v2, v2, s0
	ds_write_b16 v10, v2 offset:54528
	v_mul_f32_e32 v2, v48, v8
	v_cvt_pk_bf16_f32 v2, v2, s0
	ds_write_b16 v10, v2 offset:54592
	v_mul_f32_e32 v2, v33, v9
	v_cvt_pk_bf16_f32 v2, v2, s0
	s_lshl_b64 s[4:5], s[40:41], 11
	ds_write_b16 v10, v2 offset:54656
	v_mul_f32_e32 v2, v49, v9
	v_lshlrev_b32_e32 v0, 1, v0
	v_cvt_pk_bf16_f32 v18, v18, s0
	v_cvt_pk_bf16_f32 v11, v11, s0
	v_cvt_pk_bf16_f32 v2, v2, s0
	s_add_u32 s4, s42, s4
	v_and_b32_e32 v0, 0x70, v0
	ds_write_b16 v10, v18 offset:51200
	ds_write_b16 v10, v11 offset:53248
	ds_write_b16 v10, v2 offset:54720
	s_addc_u32 s5, s43, s5
	v_lshrrev_b32_e32 v14, 3, v226
	v_add_u32_e32 v15, s6, v0
	s_waitcnt lgkmcnt(0)
	v_lshl_add_u64 v[10:11], s[4:5], 0, v[0:1]
	v_lshl_add_u32 v0, v14, 7, v15
	v_or_b32_e32 v16, 8, v14
	ds_read_b128 v[2:5], v0 offset:51200
	v_lshl_add_u32 v6, v16, 7, v15
	ds_read_b128 v[6:9], v6 offset:51200
	v_lshlrev_b32_e32 v0, 11, v14
	v_lshl_add_u64 v[12:13], v[10:11], 0, v[0:1]
	v_lshlrev_b32_e32 v0, 11, v16
	s_waitcnt lgkmcnt(1)
	global_store_dwordx4 v[12:13], v[2:5], off
	s_nop 1
	v_lshl_add_u64 v[2:3], v[10:11], 0, v[0:1]
	v_or_b32_e32 v0, 16, v14
	s_waitcnt lgkmcnt(0)
	global_store_dwordx4 v[2:3], v[6:9], off
	v_lshl_add_u32 v2, v0, 7, v15
	v_or_b32_e32 v14, 24, v14
	ds_read_b128 v[2:5], v2 offset:51200
	v_lshl_add_u32 v6, v14, 7, v15
	ds_read_b128 v[6:9], v6 offset:51200
	v_lshlrev_b32_e32 v0, 11, v0
	v_lshl_add_u64 v[12:13], v[10:11], 0, v[0:1]
	v_lshlrev_b32_e32 v0, 11, v14
	s_waitcnt lgkmcnt(1)
	global_store_dwordx4 v[12:13], v[2:5], off
	s_nop 1
	v_lshl_add_u64 v[2:3], v[10:11], 0, v[0:1]
	s_waitcnt lgkmcnt(0)
	global_store_dwordx4 v[2:3], v[6:9], off
	s_waitcnt lgkmcnt(0)
	s_barrier

;   #define RESC() do{ if(resc){ asm volatile("s_waitcnt lgkmcnt(0)":::"memory"); \
;       _Pragma("unroll") for(int d_=0;d_<2;++d_) _Pragma("unroll") for(int r=0;r<16;++r)o[d_][r]*=wsf[crow(r,hi)]; } }while(0)
;   #define ROT() do{sl_prev=sl_cur;sl_cur=sl_next;sl_next=(sl_next==(NSLOT-1)*SLOTB)?0:sl_next+SLOTB;}while(0)
;   #define ENDW(tt) do{ if((tt)+3<NT){WAIT_BAR(2);} else if((tt)+2<NT){WAIT_BAR(1);} else {WAIT_BAR(0);} }while(0)
; template<int THRL,bool FIXREF> __device__ __forceinline__ void attn_unit(const float*gq,const float*tab,const int tq0,const bf16*Qw0,const bf16*__restrict__ Kl,const bf16*__restrict__ Vl,const int NT,bf16*Ow0,char*shm){
;     ...
;   for(;t+1<NT;t+=2){
;     STEP(pB0,pB1,pA0,pA1,t,(t+3<NT),(t+1<NT),(t+1<NT));       ENDW(t);   RESC(); ROT();
;     STEP(pA0,pA1,pB0,pB1,t+1,(t+4<NT),(t+2<NT),(t+2<NT));     ENDW(t+1); RESC(); ROT();
;   }
.LBB0_289:
	v_add_u32_e32 v51, s4, v240
	ds_read_b128 v[194:197], v51 offset:24576
	ds_read_b32 v242, v240 offset:0
	s_waitcnt lgkmcnt(9)
	v_mfma_f32_32x32x16_bf16 v[114:129], v[190:193], v[158:161], v[2:17]
	v_add_f32_e32 v52, v82, v83
	v_add_f32_e32 v52, v84, v52
	v_add_f32_e32 v52, v85, v52
	v_add_f32_e32 v52, v86, v52
	v_add_f32_e32 v52, v87, v52
	v_cvt_pk_bf16_f32 v154, v82, v83
	v_cvt_pk_bf16_f32 v155, v84, v85
	ds_read_b128 v[82:85], v51 offset:28672
	ds_read_b32 v242, v240 offset:4096
	s_waitcnt lgkmcnt(10)
	v_mfma_f32_32x32x16_bf16 v[98:113], v[186:189], v[158:161], v[2:17]
	v_add_f32_e32 v52, v88, v52
	v_add_f32_e32 v52, v89, v52
	v_add_f32_e32 v52, v90, v52
	v_add_f32_e32 v56, v91, v52
	v_cvt_pk_bf16_f32 v156, v86, v87
	v_cvt_pk_bf16_f32 v157, v88, v89
	ds_read_b128 v[52:55], v51 offset:25600
	ds_read_b32 v242, v240 offset:1024
	s_waitcnt lgkmcnt(11)
	v_mfma_f32_32x32x16_bf16 v[114:129], v[182:185], v[150:153], v[114:129]
	v_add_f32_e32 v56, v92, v56
	v_add_f32_e32 v56, v93, v56
	v_add_f32_e32 v56, v94, v56
	v_add_f32_e32 v60, v95, v56
	v_cvt_pk_bf16_f32 v146, v90, v91
	v_cvt_pk_bf16_f32 v147, v92, v93
	ds_read_b128 v[56:59], v51 offset:29696
	ds_read_b32 v242, v240 offset:5120
	s_waitcnt lgkmcnt(12)
	v_mfma_f32_32x32x16_bf16 v[98:113], v[178:181], v[150:153], v[98:113]
	v_add_f32_e32 v60, v96, v60
	v_add_f32_e32 v60, v97, v60
	v_add_f32_e32 v60, v66, v60
	v_add_f32_e32 v64, v67, v60
	v_cvt_pk_bf16_f32 v148, v94, v95
	v_cvt_pk_bf16_f32 v149, v96, v97
	ds_read_b128 v[60:63], v51 offset:26624
	ds_read_b32 v242, v240 offset:2048
	s_waitcnt lgkmcnt(13)
	v_mfma_f32_32x32x16_bf16 v[114:129], v[174:177], v[142:145], v[114:129]
	v_add_f32_e32 v64, v68, v64
	v_add_f32_e32 v64, v69, v64
	v_add_f32_e32 v64, v70, v64
	v_add_f32_e32 v86, v71, v64
	v_cvt_pk_bf16_f32 v138, v66, v67
	v_cvt_pk_bf16_f32 v139, v68, v69
	ds_read_b128 v[64:67], v51 offset:30720
	ds_read_b32 v242, v240 offset:6144
	s_waitcnt lgkmcnt(14)
	v_mfma_f32_32x32x16_bf16 v[98:113], v[170:173], v[142:145], v[98:113]
	v_add_f32_e32 v68, v72, v86
	v_add_f32_e32 v68, v73, v68
	v_add_f32_e32 v68, v74, v68
	v_add_f32_e32 v86, v75, v68
	v_cvt_pk_bf16_f32 v140, v70, v71
	v_cvt_pk_bf16_f32 v141, v72, v73
	ds_read_b128 v[68:71], v51 offset:27648
	ds_read_b32 v242, v240 offset:3072
	s_waitcnt lgkmcnt(14)
	v_mfma_f32_32x32x16_bf16 v[114:129], v[166:169], v[134:137], v[114:129]
	v_add_f32_e32 v72, v76, v86
	v_add_f32_e32 v72, v77, v72
	v_add_f32_e32 v72, v78, v72
	v_add_f32_e32 v86, v79, v72
	v_cvt_pk_bf16_f32 v130, v74, v75
	v_cvt_pk_bf16_f32 v131, v76, v77
	ds_read_b128 v[72:75], v51 offset:31744
	ds_read_b32 v242, v240 offset:7168
	v_mfma_f32_32x32x16_bf16 v[98:113], v[162:165], v[134:137], v[98:113]
	v_add_f32_e32 v51, v80, v86
	v_add_f32_e32 v51, v81, v51
	v_add_f32_e32 v51, 0, v51
	v_cvt_pk_bf16_f32 v132, v78, v79
	v_cvt_pk_bf16_f32 v133, v80, v81
	s_add_i32 s4, s10, 1
	s_cmp_ge_u32 s4, s55
	s_cselect_b64 s[4:5], -1, 0
	s_and_b64 vcc, exec, s[4:5]
	s_cbranch_vccnz .LBB0_291
	v_lshl_add_u64 v[76:77], v[212:213], 0, s[20:21]
	s_add_i32 s6, s30, s18
	s_mov_b32 s7, m0
	s_mov_b32 m0, s6
	s_nop 0
	global_load_lds_dwordx4 v[76:77], off
	s_mov_b32 m0, s7

;   #define RESC() do{ if(resc){ asm volatile("s_waitcnt lgkmcnt(0)":::"memory"); \
;       _Pragma("unroll") for(int d_=0;d_<2;++d_) _Pragma("unroll") for(int r=0;r<16;++r)o[d_][r]*=wsf[crow(r,hi)]; } }while(0)
;   #define ROT() do{sl_prev=sl_cur;sl_cur=sl_next;sl_next=(sl_next==(NSLOT-1)*SLOTB)?0:sl_next+SLOTB;}while(0)
;   #define ENDW(tt) do{ if((tt)+3<NT){WAIT_BAR(2);} else if((tt)+2<NT){WAIT_BAR(1);} else {WAIT_BAR(0);} }while(0)
; template<int THRL,bool FIXREF> __device__ __forceinline__ void attn_unit(const float*gq,const float*tab,const int tq0,const bf16*Qw0,const bf16*__restrict__ Kl,const bf16*__restrict__ Vl,const int NT,bf16*Ow0,char*shm){
;     ...
;   for(;t+1<NT;t+=2){
;     STEP(pB0,pB1,pA0,pA1,t,(t+3<NT),(t+1<NT),(t+1<NT));       ENDW(t);   RESC(); ROT();
;     STEP(pA0,pA1,pB0,pB1,t+1,(t+4<NT),(t+2<NT),(t+2<NT));     ENDW(t+1); RESC(); ROT();
;   }
.LBB0_299:
	v_add_u32_e32 v54, s30, v240
	ds_read_b128 v[202:205], v54 offset:24576
	ds_read_b32 v242, v240 offset:0
	s_waitcnt lgkmcnt(9)
	v_mfma_f32_32x32x16_bf16 v[82:97], v[190:193], v[158:161], v[2:17]
	v_add_f32_e32 v52, v114, v115
	v_add_f32_e32 v52, v116, v52
	v_add_f32_e32 v52, v117, v52
	v_add_f32_e32 v52, v118, v52
	v_add_f32_e32 v52, v119, v52
	v_cvt_pk_bf16_f32 v154, v114, v115
	v_cvt_pk_bf16_f32 v155, v116, v117
	ds_read_b128 v[198:201], v54 offset:28672
	ds_read_b32 v242, v240 offset:4096
	s_waitcnt lgkmcnt(10)
	v_mfma_f32_32x32x16_bf16 v[66:81], v[186:189], v[158:161], v[2:17]
	v_add_f32_e32 v52, v120, v52
	v_add_f32_e32 v52, v121, v52
	v_add_f32_e32 v52, v122, v52
	v_add_f32_e32 v52, v123, v52
	v_cvt_pk_bf16_f32 v156, v118, v119
	v_cvt_pk_bf16_f32 v157, v120, v121
	ds_read_b128 v[194:197], v54 offset:25600
	ds_read_b32 v242, v240 offset:1024
	s_waitcnt lgkmcnt(11)
	v_mfma_f32_32x32x16_bf16 v[82:97], v[182:185], v[150:153], v[82:97]
	v_add_f32_e32 v52, v124, v52
	v_add_f32_e32 v52, v125, v52
	v_add_f32_e32 v52, v126, v52
	v_add_f32_e32 v52, v127, v52
	v_cvt_pk_bf16_f32 v146, v122, v123
	v_cvt_pk_bf16_f32 v147, v124, v125
	ds_read_b128 v[118:121], v54 offset:29696
	ds_read_b32 v242, v240 offset:5120
	s_waitcnt lgkmcnt(12)
	v_mfma_f32_32x32x16_bf16 v[66:81], v[178:181], v[150:153], v[66:81]
	v_add_f32_e32 v52, v128, v52
	v_add_f32_e32 v52, v129, v52
	v_add_f32_e32 v52, v98, v52
	v_add_f32_e32 v52, v99, v52
	v_cvt_pk_bf16_f32 v148, v126, v127
	v_cvt_pk_bf16_f32 v149, v128, v129
	ds_read_b128 v[114:117], v54 offset:26624
	ds_read_b32 v242, v240 offset:2048
	s_waitcnt lgkmcnt(13)
	v_mfma_f32_32x32x16_bf16 v[82:97], v[174:177], v[142:145], v[82:97]
	v_add_f32_e32 v52, v100, v52
	v_add_f32_e32 v52, v101, v52
	v_add_f32_e32 v52, v102, v52
	v_add_f32_e32 v52, v103, v52
	v_cvt_pk_bf16_f32 v138, v98, v99
	v_cvt_pk_bf16_f32 v139, v100, v101
	ds_read_b128 v[60:63], v54 offset:30720
	ds_read_b32 v242, v240 offset:6144
	s_waitcnt lgkmcnt(14)
	v_mfma_f32_32x32x16_bf16 v[66:81], v[170:173], v[142:145], v[66:81]
	v_add_f32_e32 v52, v104, v52
	v_add_f32_e32 v52, v105, v52
	v_add_f32_e32 v52, v106, v52
	v_add_f32_e32 v52, v107, v52
	v_cvt_pk_bf16_f32 v140, v102, v103
	v_cvt_pk_bf16_f32 v141, v104, v105
	ds_read_b128 v[56:59], v54 offset:27648
	ds_read_b32 v242, v240 offset:3072
	s_waitcnt lgkmcnt(14)
	v_mfma_f32_32x32x16_bf16 v[82:97], v[166:169], v[134:137], v[82:97]
	v_add_f32_e32 v52, v108, v52
	v_add_f32_e32 v52, v109, v52
	v_add_f32_e32 v52, v110, v52
	v_add_f32_e32 v64, v111, v52
	v_cvt_pk_bf16_f32 v130, v106, v107
	v_cvt_pk_bf16_f32 v131, v108, v109
	ds_read_b128 v[52:55], v54 offset:31744
	ds_read_b32 v242, v240 offset:7168
	v_mfma_f32_32x32x16_bf16 v[66:81], v[162:165], v[134:137], v[66:81]
	v_add_f32_e32 v64, v112, v64
	v_add_f32_e32 v64, v113, v64
	v_add_f32_e32 v64, 0, v64
	v_cvt_pk_bf16_f32 v132, v110, v111
	v_cvt_pk_bf16_f32 v133, v112, v113
	s_add_i32 s47, s10, 2
	s_cmp_ge_u32 s47, s55
	s_cselect_b64 s[6:7], -1, 0
	s_and_b64 vcc, exec, s[6:7]
	s_cbranch_vccnz .LBB0_301
	s_add_i32 s14, s31, s18
	s_mov_b32 s15, m0
	s_mov_b32 m0, s14
	s_nop 0
	global_load_lds_dwordx4 v[212:213], off
	s_mov_b32 m0, s15

; __global__ void __launch_bounds__(512, 2) fwd_megakernel(Args args) {
;     ...
;             for (int m = gw; m < M_ALL; m += NGW) {
;                 PostRaw nxt = cur; const int mn = m + NGW;
;                 if (mn < M_ALL) POST_LOAD(nxt, mn);
;                 u16* rowp = P + (size_t)m * NPAD;
;                 const int kvb = m < M_LAT ? (m >> 14) : ((m - M_LAT) >> 8), kvt = m < M_LAT ? ((m & 16383) >> 6) : 256 + (((m - M_LAT) & 255) >> 6), kvr = m & 63;
;                 const size_t kvbase = ((size_t)(kvb * 2) * 260 + kvt) * 4096;
;     ...
;                     if (lane < 16) { const int cc = (lane & 7) * 8, vw_ = (cc >> 5) * 4 + (kvr >> 4), vl_ = (kvr & 15) * 4 + ((cc & 31) >> 3);
;                         *(u32x4*)(VB + kvbase + (size_t)(lane >> 3) * (260 * 4096) + (vw_ * 64 + vl_) * 8) = cur.av; }
.Lvt_entry:
	v_readfirstlane_b32 s10, v214
	v_readlane_b32 s14, v239, 4
	v_and_b32_e32 v2, 63, v214
	v_lshlrev_b32_e32 v3, 1, v2
	v_lshrrev_b32_e32 v40, 5, v2
	v_and_b32_e32 v41, 31, v2
	s_nop 3
	s_ashr_i32 s10, s10, 6
	s_add_i32 s10, s10, s14
	v_add_u32_e32 v3, 0x1100, v3
	v_lshlrev_b32_e32 v40, 12, v40
	v_lshl_add_u32 v40, v41, 4, v40
.Lvt_loop:
	s_cmpk_ge_i32 s10, 0x1040
	s_cbranch_scc1 .LBB0_373
	s_lshr_b32 s14, s10, 1
	s_and_b32 s15, s10, 1
	s_lshl_b32 s18, s14, 4
	s_mul_i32 s19, s18, 0x1400
	s_lshl_b32 s22, s15, 7
	s_add_i32 s19, s19, s22
	s_add_u32 s22, s58, 0x7400000
	s_addc_u32 s23, s59, 0
	s_add_u32 s22, s22, s19
	s_addc_u32 s23, s23, 0
	global_load_ushort v4, v3, s[22:23]
	s_add_u32 s22, s22, 0x1400
	s_addc_u32 s23, s23, 0
	global_load_ushort v5, v3, s[22:23]
	s_add_u32 s22, s22, 0x1400
	s_addc_u32 s23, s23, 0
	global_load_ushort v6, v3, s[22:23]
	s_add_u32 s22, s22, 0x1400
	s_addc_u32 s23, s23, 0
	global_load_ushort v7, v3, s[22:23]
	s_add_u32 s22, s22, 0x1400
	s_addc_u32 s23, s23, 0
	global_load_ushort v8, v3, s[22:23]
	s_add_u32 s22, s22, 0x1400
	s_addc_u32 s23, s23, 0
	global_load_ushort v9, v3, s[22:23]
	s_add_u32 s22, s22, 0x1400
	s_addc_u32 s23, s23, 0
	global_load_ushort v10, v3, s[22:23]
	s_add_u32 s22, s22, 0x1400
	s_addc_u32 s23, s23, 0
	global_load_ushort v11, v3, s[22:23]
	s_add_u32 s22, s22, 0x1400
	s_addc_u32 s23, s23, 0
	global_load_ushort v12, v3, s[22:23]
	s_add_u32 s22, s22, 0x1400
	s_addc_u32 s23, s23, 0
	global_load_ushort v13, v3, s[22:23]
	s_add_u32 s22, s22, 0x1400
	s_addc_u32 s23, s23, 0
	global_load_ushort v14, v3, s[22:23]
	s_add_u32 s22, s22, 0x1400
	s_addc_u32 s23, s23, 0
	global_load_ushort v15, v3, s[22:23]
	s_add_u32 s22, s22, 0x1400
	s_addc_u32 s23, s23, 0
	global_load_ushort v16, v3, s[22:23]
	s_add_u32 s22, s22, 0x1400
	s_addc_u32 s23, s23, 0
	global_load_ushort v17, v3, s[22:23]
	s_add_u32 s22, s22, 0x1400
	s_addc_u32 s23, s23, 0
	global_load_ushort v18, v3, s[22:23]
	s_add_u32 s22, s22, 0x1400
	s_addc_u32 s23, s23, 0
	global_load_ushort v19, v3, s[22:23]
	s_sub_i32 s27, s18, 0x8000
	s_lshr_b32 s28, s18, 14
	s_bfe_u32 s29, s18, 0x80006
	s_lshr_b32 s4, s27, 8
	s_bfe_u32 s5, s27, 0x20006
	s_addk_i32 s5, 0x100
	s_cmp_lt_u32 s18, 0x8000
	s_cselect_b32 s28, s28, s4
	s_cselect_b32 s29, s29, s5
	s_lshl_b32 s28, s28, 1
	s_add_i32 s28, s28, s15
	s_mul_i32 s28, s28, 0x104
	s_add_i32 s28, s28, s29
	s_lshl_b32 s28, s28, 13
	s_bfe_u32 s29, s18, 0x20004
	s_lshl_b32 s29, s29, 10
	s_add_i32 s28, s28, s29
	s_add_u32 s4, s58, 0x11680000
	s_addc_u32 s5, s59, 0
	s_add_u32 s4, s4, s28
	s_addc_u32 s5, s5, 0
	s_waitcnt vmcnt(0)
	v_lshl_or_b32 v20, v5, 16, v4
	v_lshl_or_b32 v21, v7, 16, v6
	v_lshl_or_b32 v22, v13, 16, v12
	v_lshl_or_b32 v23, v15, 16, v14
	v_lshl_or_b32 v24, v9, 16, v8
	v_lshl_or_b32 v25, v11, 16, v10
	v_lshl_or_b32 v26, v17, 16, v16
	v_lshl_or_b32 v27, v19, 16, v18
	global_store_dwordx4 v40, v[20:23], s[4:5]
	global_store_dwordx4 v40, v[24:27], s[4:5] offset:512
	s_add_i32 s10, s10, s64
	s_branch .Lvt_loop
